# decay lora epilogue rewritten by hand in f32 (log(1+u) via v_log_f32); gates sigmoid uses v_rcp_f32 instead of IEEE div sequence
# speedup vs baseline: 1.0477x; 1.0477x over previous
; DI float softplusf_(float x) { return fmaxf(x, 0.f) + log1pf(__expf(-fabsf(x))); }
;   DI void operator()(const Acc8& acc, const pg8::Unit& u, int wr, int wc, int fr, int fq) const {
;     ...
;       for (int bj = 0; bj < 2; ++bj) {
;         const int c8 = bj * 128 + wc * 32 + 8 * fq;
;         const float4 w0a = *(const float4*)(w0 + c8), w0b = *(const float4*)(w0 + c8 + 4);
; #pragma unroll
;         for (int ai = 0; ai < 2; ++ai)
; #pragma unroll
;           for (int m = 0; m < 4; ++m) {
;             const size_t o = (size_t)EPI_ROWS(ai, m) * 256 + c8;
;             const f32x4 x0 = acc[ai][bj][m][0], x1 = acc[ai][bj][m][1];
;             float4 d0, d1;
;             d0.x = __expf(-__expf(-softplusf_(-(w0a.x + x0[0])) - 0.5f)); d0.y = __expf(-__expf(-softplusf_(-(w0a.y + x0[1])) - 0.5f));
;             d0.z = __expf(-__expf(-softplusf_(-(w0a.z + x0[2])) - 0.5f)); d0.w = __expf(-__expf(-softplusf_(-(w0a.w + x0[3])) - 0.5f));
;             d1.x = __expf(-__expf(-softplusf_(-(w0b.x + x1[0])) - 0.5f)); d1.y = __expf(-__expf(-softplusf_(-(w0b.y + x1[1])) - 0.5f));
;             d1.z = __expf(-__expf(-softplusf_(-(w0b.z + x1[2])) - 0.5f)); d1.w = __expf(-__expf(-softplusf_(-(w0b.w + x1[3])) - 0.5f));
;             *(float4*)(sW + o) = d0; *(float4*)(sW + o + 4) = d1;
;             asm volatile("" ::: "memory"); __builtin_amdgcn_sched_barrier(0);
;           }
.LBB0_492:
	s_andn2_b64 vcc, exec, s[14:15]
	s_cbranch_vccnz .LBB0_494
	s_add_u32 s2, s2, 0x10ea0000
	s_addc_u32 s3, s3, 0
	s_add_u32 s6, s10, s8
	s_addc_u32 s7, s11, s9
	s_lshl_b64 s[4:5], s[64:65], 2
	s_add_u32 s4, s6, s4
	s_addc_u32 s5, s7, s5
	v_lshlrev_b64 v[146:147], 2, v[192:193]
	v_lshl_add_u64 v[142:143], s[4:5], 0, v[146:147]
	global_load_dwordx4 v[130:133], v[142:143], off offset:16
	global_load_dwordx4 v[134:137], v[142:143], off
	global_load_dwordx4 v[34:37], v[142:143], off offset:528
	global_load_dwordx4 v[30:33], v[142:143], off offset:512
	s_mov_b32 s4, 0xbfb8aa3b
	s_mov_b32 s5, 0x3f317218
	v_mov_b32_e32 v0, 0xbf38aa3b
	s_waitcnt vmcnt(0)
	v_lshlrev_b64 v[142:143], 10, v[190:191]
	v_lshl_add_u64 v[142:143], s[2:3], 0, v[142:143]
	v_lshl_add_u64 v[142:143], v[142:143], 0, v[146:147]
	v_add_f32_e32 v126, v126, v134
	v_add_f32_e32 v127, v127, v135
	v_add_f32_e32 v128, v128, v136
	v_add_f32_e32 v129, v129, v137
	v_mul_f32_e64 v160, |v126|, s4
	v_mul_f32_e64 v161, |v127|, s4
	v_mul_f32_e64 v162, |v128|, s4
	v_mul_f32_e64 v139, |v129|, s4
	v_max_f32_e64 v126, -v126, 0
	v_max_f32_e64 v127, -v127, 0
	v_max_f32_e64 v128, -v128, 0
	v_max_f32_e64 v129, -v129, 0
	v_exp_f32_e32 v160, v160
	v_exp_f32_e32 v161, v161
	v_exp_f32_e32 v162, v162
	v_exp_f32_e32 v139, v139
	v_add_f32_e32 v160, 1.0, v160
	v_add_f32_e32 v161, 1.0, v161
	v_add_f32_e32 v162, 1.0, v162
	v_add_f32_e32 v139, 1.0, v139
	v_log_f32_e32 v160, v160
	v_log_f32_e32 v161, v161
	v_log_f32_e32 v162, v162
	v_log_f32_e32 v139, v139
	v_fma_f32 v126, v160, s5, v126
	v_fma_f32 v127, v161, s5, v127
	v_fma_f32 v128, v162, s5, v128
	v_fma_f32 v129, v139, s5, v129
	v_fma_f32 v126, v126, s4, v0
	v_fma_f32 v127, v127, s4, v0
	v_fma_f32 v128, v128, s4, v0
	v_fma_f32 v129, v129, s4, v0
	v_exp_f32_e32 v126, v126
	v_exp_f32_e32 v127, v127
	v_exp_f32_e32 v128, v128
	v_exp_f32_e32 v129, v129
	v_mul_f32_e32 v126, s4, v126
	v_mul_f32_e32 v127, s4, v127
	v_mul_f32_e32 v128, s4, v128
	v_mul_f32_e32 v129, s4, v129
	v_exp_f32_e32 v126, v126
	v_exp_f32_e32 v127, v127
	v_exp_f32_e32 v128, v128
	v_exp_f32_e32 v129, v129
	s_nop 1
	global_store_dwordx4 v[142:143], v[126:129], off
	v_add_f32_e32 v122, v122, v130
	v_add_f32_e32 v123, v123, v131
	v_add_f32_e32 v124, v124, v132
	v_add_f32_e32 v125, v125, v133
	v_mul_f32_e64 v160, |v122|, s4
	v_mul_f32_e64 v161, |v123|, s4
	v_mul_f32_e64 v162, |v124|, s4
	v_mul_f32_e64 v139, |v125|, s4
	v_max_f32_e64 v122, -v122, 0
	v_max_f32_e64 v123, -v123, 0
	v_max_f32_e64 v124, -v124, 0
	v_max_f32_e64 v125, -v125, 0
	v_exp_f32_e32 v160, v160
	v_exp_f32_e32 v161, v161
	v_exp_f32_e32 v162, v162
	v_exp_f32_e32 v139, v139
	v_add_f32_e32 v160, 1.0, v160
	v_add_f32_e32 v161, 1.0, v161
	v_add_f32_e32 v162, 1.0, v162
	v_add_f32_e32 v139, 1.0, v139
	v_log_f32_e32 v160, v160
	v_log_f32_e32 v161, v161
	v_log_f32_e32 v162, v162
	v_log_f32_e32 v139, v139
	v_fma_f32 v122, v160, s5, v122
	v_fma_f32 v123, v161, s5, v123
	v_fma_f32 v124, v162, s5, v124
	v_fma_f32 v125, v139, s5, v125
	v_fma_f32 v122, v122, s4, v0
	v_fma_f32 v123, v123, s4, v0
	v_fma_f32 v124, v124, s4, v0
	v_fma_f32 v125, v125, s4, v0
	v_exp_f32_e32 v122, v122
	v_exp_f32_e32 v123, v123
	v_exp_f32_e32 v124, v124
	v_exp_f32_e32 v125, v125
	v_mul_f32_e32 v122, s4, v122
	v_mul_f32_e32 v123, s4, v123
	v_mul_f32_e32 v124, s4, v124
	v_mul_f32_e32 v125, s4, v125
	v_exp_f32_e32 v122, v122
	v_exp_f32_e32 v123, v123
	v_exp_f32_e32 v124, v124
	v_exp_f32_e32 v125, v125
	s_nop 1
	global_store_dwordx4 v[142:143], v[122:125], off offset:16
	v_add_f32_e32 v62, v62, v30
	v_add_f32_e32 v63, v63, v31
	v_add_f32_e32 v64, v64, v32
	v_add_f32_e32 v65, v65, v33
	v_mul_f32_e64 v160, |v62|, s4
	v_mul_f32_e64 v161, |v63|, s4
	v_mul_f32_e64 v162, |v64|, s4
	v_mul_f32_e64 v139, |v65|, s4
	v_max_f32_e64 v62, -v62, 0
	v_max_f32_e64 v63, -v63, 0
	v_max_f32_e64 v64, -v64, 0
	v_max_f32_e64 v65, -v65, 0
	v_exp_f32_e32 v160, v160
	v_exp_f32_e32 v161, v161
	v_exp_f32_e32 v162, v162
	v_exp_f32_e32 v139, v139
	v_add_f32_e32 v160, 1.0, v160
	v_add_f32_e32 v161, 1.0, v161
	v_add_f32_e32 v162, 1.0, v162
	v_add_f32_e32 v139, 1.0, v139
	v_log_f32_e32 v160, v160
	v_log_f32_e32 v161, v161
	v_log_f32_e32 v162, v162
	v_log_f32_e32 v139, v139
	v_fma_f32 v62, v160, s5, v62
	v_fma_f32 v63, v161, s5, v63
	v_fma_f32 v64, v162, s5, v64
	v_fma_f32 v65, v139, s5, v65
	v_fma_f32 v62, v62, s4, v0
	v_fma_f32 v63, v63, s4, v0
	v_fma_f32 v64, v64, s4, v0
	v_fma_f32 v65, v65, s4, v0
	v_exp_f32_e32 v62, v62
	v_exp_f32_e32 v63, v63
	v_exp_f32_e32 v64, v64
	v_exp_f32_e32 v65, v65
	v_mul_f32_e32 v62, s4, v62
	v_mul_f32_e32 v63, s4, v63
	v_mul_f32_e32 v64, s4, v64
	v_mul_f32_e32 v65, s4, v65
	v_exp_f32_e32 v62, v62
	v_exp_f32_e32 v63, v63
	v_exp_f32_e32 v64, v64
	v_exp_f32_e32 v65, v65
	s_nop 1
	global_store_dwordx4 v[142:143], v[62:65], off offset:512
	v_add_f32_e32 v58, v58, v34
	v_add_f32_e32 v59, v59, v35
	v_add_f32_e32 v60, v60, v36
	v_add_f32_e32 v61, v61, v37
	v_mul_f32_e64 v160, |v58|, s4
	v_mul_f32_e64 v161, |v59|, s4
	v_mul_f32_e64 v162, |v60|, s4
	v_mul_f32_e64 v139, |v61|, s4
	v_max_f32_e64 v58, -v58, 0
	v_max_f32_e64 v59, -v59, 0
	v_max_f32_e64 v60, -v60, 0
	v_max_f32_e64 v61, -v61, 0
	v_exp_f32_e32 v160, v160
	v_exp_f32_e32 v161, v161
	v_exp_f32_e32 v162, v162
	v_exp_f32_e32 v139, v139
	v_add_f32_e32 v160, 1.0, v160
	v_add_f32_e32 v161, 1.0, v161
	v_add_f32_e32 v162, 1.0, v162
	v_add_f32_e32 v139, 1.0, v139
	v_log_f32_e32 v160, v160
	v_log_f32_e32 v161, v161
	v_log_f32_e32 v162, v162
	v_log_f32_e32 v139, v139
	v_fma_f32 v58, v160, s5, v58
	v_fma_f32 v59, v161, s5, v59
	v_fma_f32 v60, v162, s5, v60
	v_fma_f32 v61, v139, s5, v61
	v_fma_f32 v58, v58, s4, v0
; DI float softplusf_(float x) { return fmaxf(x, 0.f) + log1pf(__expf(-fabsf(x))); }
;   DI void operator()(const Acc8& acc, const pg8::Unit& u, int wr, int wc, int fr, int fq) const {
;     ...
;           for (int m = 0; m < 4; ++m) {
;             const size_t o = (size_t)EPI_ROWS(ai, m) * 256 + c8;
;             const f32x4 x0 = acc[ai][bj][m][0], x1 = acc[ai][bj][m][1];
;             float4 d0, d1;
;             d0.x = __expf(-__expf(-softplusf_(-(w0a.x + x0[0])) - 0.5f)); d0.y = __expf(-__expf(-softplusf_(-(w0a.y + x0[1])) - 0.5f));
;             d0.z = __expf(-__expf(-softplusf_(-(w0a.z + x0[2])) - 0.5f)); d0.w = __expf(-__expf(-softplusf_(-(w0a.w + x0[3])) - 0.5f));
;             d1.x = __expf(-__expf(-softplusf_(-(w0b.x + x1[0])) - 0.5f)); d1.y = __expf(-__expf(-softplusf_(-(w0b.y + x1[1])) - 0.5f));
;             d1.z = __expf(-__expf(-softplusf_(-(w0b.z + x1[2])) - 0.5f)); d1.w = __expf(-__expf(-softplusf_(-(w0b.w + x1[3])) - 0.5f));
;             *(float4*)(sW + o) = d0; *(float4*)(sW + o + 4) = d1;
;             asm volatile("" ::: "memory"); __builtin_amdgcn_sched_barrier(0);
;           }
	v_fma_f32 v59, v59, s4, v0
	v_fma_f32 v60, v60, s4, v0
	v_fma_f32 v61, v61, s4, v0
	v_exp_f32_e32 v58, v58
	v_exp_f32_e32 v59, v59
	v_exp_f32_e32 v60, v60
	v_exp_f32_e32 v61, v61
	v_mul_f32_e32 v58, s4, v58
	v_mul_f32_e32 v59, s4, v59
	v_mul_f32_e32 v60, s4, v60
	v_mul_f32_e32 v61, s4, v61
	v_exp_f32_e32 v58, v58
	v_exp_f32_e32 v59, v59
	v_exp_f32_e32 v60, v60
	v_exp_f32_e32 v61, v61
	s_nop 1
	global_store_dwordx4 v[142:143], v[58:61], off offset:528
	v_lshlrev_b64 v[144:145], 10, v[158:159]
	v_lshl_add_u64 v[144:145], s[2:3], 0, v[144:145]
	v_lshl_add_u64 v[144:145], v[144:145], 0, v[146:147]
	v_add_f32_e32 v118, v118, v134
	v_add_f32_e32 v119, v119, v135
	v_add_f32_e32 v120, v120, v136
	v_add_f32_e32 v121, v121, v137
	v_mul_f32_e64 v160, |v118|, s4
	v_mul_f32_e64 v161, |v119|, s4
	v_mul_f32_e64 v162, |v120|, s4
	v_mul_f32_e64 v139, |v121|, s4
	v_max_f32_e64 v118, -v118, 0
	v_max_f32_e64 v119, -v119, 0
	v_max_f32_e64 v120, -v120, 0
	v_max_f32_e64 v121, -v121, 0
	v_exp_f32_e32 v160, v160
	v_exp_f32_e32 v161, v161
	v_exp_f32_e32 v162, v162
	v_exp_f32_e32 v139, v139
	v_add_f32_e32 v160, 1.0, v160
	v_add_f32_e32 v161, 1.0, v161
	v_add_f32_e32 v162, 1.0, v162
	v_add_f32_e32 v139, 1.0, v139
	v_log_f32_e32 v160, v160
	v_log_f32_e32 v161, v161
	v_log_f32_e32 v162, v162
	v_log_f32_e32 v139, v139
	v_fma_f32 v118, v160, s5, v118
	v_fma_f32 v119, v161, s5, v119
	v_fma_f32 v120, v162, s5, v120
	v_fma_f32 v121, v139, s5, v121
	v_fma_f32 v118, v118, s4, v0
	v_fma_f32 v119, v119, s4, v0
	v_fma_f32 v120, v120, s4, v0
	v_fma_f32 v121, v121, s4, v0
	v_exp_f32_e32 v118, v118
	v_exp_f32_e32 v119, v119
	v_exp_f32_e32 v120, v120
	v_exp_f32_e32 v121, v121
	v_mul_f32_e32 v118, s4, v118
	v_mul_f32_e32 v119, s4, v119
	v_mul_f32_e32 v120, s4, v120
	v_mul_f32_e32 v121, s4, v121
	v_exp_f32_e32 v118, v118
	v_exp_f32_e32 v119, v119
	v_exp_f32_e32 v120, v120
	v_exp_f32_e32 v121, v121
	s_nop 1
	global_store_dwordx4 v[144:145], v[118:121], off
	v_add_f32_e32 v114, v114, v130
	v_add_f32_e32 v115, v115, v131
	v_add_f32_e32 v116, v116, v132
	v_add_f32_e32 v117, v117, v133
	v_mul_f32_e64 v160, |v114|, s4
	v_mul_f32_e64 v161, |v115|, s4
	v_mul_f32_e64 v162, |v116|, s4
	v_mul_f32_e64 v139, |v117|, s4
	v_max_f32_e64 v114, -v114, 0
	v_max_f32_e64 v115, -v115, 0
	v_max_f32_e64 v116, -v116, 0
	v_max_f32_e64 v117, -v117, 0
	v_exp_f32_e32 v160, v160
	v_exp_f32_e32 v161, v161
	v_exp_f32_e32 v162, v162
	v_exp_f32_e32 v139, v139
	v_add_f32_e32 v160, 1.0, v160
	v_add_f32_e32 v161, 1.0, v161
	v_add_f32_e32 v162, 1.0, v162
	v_add_f32_e32 v139, 1.0, v139
	v_log_f32_e32 v160, v160
	v_log_f32_e32 v161, v161
	v_log_f32_e32 v162, v162
	v_log_f32_e32 v139, v139
	v_fma_f32 v114, v160, s5, v114
	v_fma_f32 v115, v161, s5, v115
	v_fma_f32 v116, v162, s5, v116
	v_fma_f32 v117, v139, s5, v117
	v_fma_f32 v114, v114, s4, v0
	v_fma_f32 v115, v115, s4, v0
	v_fma_f32 v116, v116, s4, v0
	v_fma_f32 v117, v117, s4, v0
	v_exp_f32_e32 v114, v114
	v_exp_f32_e32 v115, v115
	v_exp_f32_e32 v116, v116
	v_exp_f32_e32 v117, v117
	v_mul_f32_e32 v114, s4, v114
	v_mul_f32_e32 v115, s4, v115
	v_mul_f32_e32 v116, s4, v116
	v_mul_f32_e32 v117, s4, v117
	v_exp_f32_e32 v114, v114
	v_exp_f32_e32 v115, v115
	v_exp_f32_e32 v116, v116
	v_exp_f32_e32 v117, v117
	s_nop 1
	global_store_dwordx4 v[144:145], v[114:117], off offset:16
	v_add_f32_e32 v54, v54, v30
	v_add_f32_e32 v55, v55, v31
	v_add_f32_e32 v56, v56, v32
	v_add_f32_e32 v57, v57, v33
	v_mul_f32_e64 v160, |v54|, s4
	v_mul_f32_e64 v161, |v55|, s4
	v_mul_f32_e64 v162, |v56|, s4
	v_mul_f32_e64 v139, |v57|, s4
	v_max_f32_e64 v54, -v54, 0
	v_max_f32_e64 v55, -v55, 0
	v_max_f32_e64 v56, -v56, 0
	v_max_f32_e64 v57, -v57, 0
	v_exp_f32_e32 v160, v160
	v_exp_f32_e32 v161, v161
	v_exp_f32_e32 v162, v162
	v_exp_f32_e32 v139, v139
	v_add_f32_e32 v160, 1.0, v160
	v_add_f32_e32 v161, 1.0, v161
	v_add_f32_e32 v162, 1.0, v162
	v_add_f32_e32 v139, 1.0, v139
	v_log_f32_e32 v160, v160
	v_log_f32_e32 v161, v161
	v_log_f32_e32 v162, v162
	v_log_f32_e32 v139, v139
	v_fma_f32 v54, v160, s5, v54
	v_fma_f32 v55, v161, s5, v55
	v_fma_f32 v56, v162, s5, v56
	v_fma_f32 v57, v139, s5, v57
	v_fma_f32 v54, v54, s4, v0
	v_fma_f32 v55, v55, s4, v0
	v_fma_f32 v56, v56, s4, v0
	v_fma_f32 v57, v57, s4, v0
	v_exp_f32_e32 v54, v54
	v_exp_f32_e32 v55, v55
	v_exp_f32_e32 v56, v56
	v_exp_f32_e32 v57, v57
	v_mul_f32_e32 v54, s4, v54
	v_mul_f32_e32 v55, s4, v55
	v_mul_f32_e32 v56, s4, v56
	v_mul_f32_e32 v57, s4, v57
	v_exp_f32_e32 v54, v54
	v_exp_f32_e32 v55, v55
	v_exp_f32_e32 v56, v56
	v_exp_f32_e32 v57, v57
	s_nop 1
	global_store_dwordx4 v[144:145], v[54:57], off offset:512
	v_add_f32_e32 v50, v50, v34
	v_add_f32_e32 v51, v51, v35
	v_add_f32_e32 v52, v52, v36
	v_add_f32_e32 v53, v53, v37
	v_mul_f32_e64 v160, |v50|, s4
	v_mul_f32_e64 v161, |v51|, s4
	v_mul_f32_e64 v162, |v52|, s4
	v_mul_f32_e64 v139, |v53|, s4
	v_max_f32_e64 v50, -v50, 0
	v_max_f32_e64 v51, -v51, 0
	v_max_f32_e64 v52, -v52, 0
	v_max_f32_e64 v53, -v53, 0
	v_exp_f32_e32 v160, v160
	v_exp_f32_e32 v161, v161
	v_exp_f32_e32 v162, v162
	v_exp_f32_e32 v139, v139
	v_add_f32_e32 v160, 1.0, v160
	v_add_f32_e32 v161, 1.0, v161
	v_add_f32_e32 v162, 1.0, v162
	v_add_f32_e32 v139, 1.0, v139
	v_log_f32_e32 v160, v160
	v_log_f32_e32 v161, v161
	v_log_f32_e32 v162, v162
	v_log_f32_e32 v139, v139
	v_fma_f32 v50, v160, s5, v50
	v_fma_f32 v51, v161, s5, v51
	v_fma_f32 v52, v162, s5, v52
	v_fma_f32 v53, v139, s5, v53
	v_fma_f32 v50, v50, s4, v0
	v_fma_f32 v51, v51, s4, v0
	v_fma_f32 v52, v52, s4, v0
	v_fma_f32 v53, v53, s4, v0
	v_exp_f32_e32 v50, v50
	v_exp_f32_e32 v51, v51
	v_exp_f32_e32 v52, v52
	v_exp_f32_e32 v53, v53
	v_mul_f32_e32 v50, s4, v50
; DI float softplusf_(float x) { return fmaxf(x, 0.f) + log1pf(__expf(-fabsf(x))); }
;   DI void operator()(const Acc8& acc, const pg8::Unit& u, int wr, int wc, int fr, int fq) const {
;     ...
;           for (int m = 0; m < 4; ++m) {
;             const size_t o = (size_t)EPI_ROWS(ai, m) * 256 + c8;
;             const f32x4 x0 = acc[ai][bj][m][0], x1 = acc[ai][bj][m][1];
;             float4 d0, d1;
;             d0.x = __expf(-__expf(-softplusf_(-(w0a.x + x0[0])) - 0.5f)); d0.y = __expf(-__expf(-softplusf_(-(w0a.y + x0[1])) - 0.5f));
;             d0.z = __expf(-__expf(-softplusf_(-(w0a.z + x0[2])) - 0.5f)); d0.w = __expf(-__expf(-softplusf_(-(w0a.w + x0[3])) - 0.5f));
;             d1.x = __expf(-__expf(-softplusf_(-(w0b.x + x1[0])) - 0.5f)); d1.y = __expf(-__expf(-softplusf_(-(w0b.y + x1[1])) - 0.5f));
;             d1.z = __expf(-__expf(-softplusf_(-(w0b.z + x1[2])) - 0.5f)); d1.w = __expf(-__expf(-softplusf_(-(w0b.w + x1[3])) - 0.5f));
;             *(float4*)(sW + o) = d0; *(float4*)(sW + o + 4) = d1;
;             asm volatile("" ::: "memory"); __builtin_amdgcn_sched_barrier(0);
;           }
	v_mul_f32_e32 v51, s4, v51
	v_mul_f32_e32 v52, s4, v52
	v_mul_f32_e32 v53, s4, v53
	v_exp_f32_e32 v50, v50
	v_exp_f32_e32 v51, v51
	v_exp_f32_e32 v52, v52
	v_exp_f32_e32 v53, v53
	s_nop 1
	global_store_dwordx4 v[144:145], v[50:53], off offset:528
	v_lshlrev_b64 v[142:143], 10, v[156:157]
	v_lshl_add_u64 v[142:143], s[2:3], 0, v[142:143]
	v_lshl_add_u64 v[142:143], v[142:143], 0, v[146:147]
	v_add_f32_e32 v110, v110, v134
	v_add_f32_e32 v111, v111, v135
	v_add_f32_e32 v112, v112, v136
	v_add_f32_e32 v113, v113, v137
	v_mul_f32_e64 v160, |v110|, s4
	v_mul_f32_e64 v161, |v111|, s4
	v_mul_f32_e64 v162, |v112|, s4
	v_mul_f32_e64 v139, |v113|, s4
	v_max_f32_e64 v110, -v110, 0
	v_max_f32_e64 v111, -v111, 0
	v_max_f32_e64 v112, -v112, 0
	v_max_f32_e64 v113, -v113, 0
	v_exp_f32_e32 v160, v160
	v_exp_f32_e32 v161, v161
	v_exp_f32_e32 v162, v162
	v_exp_f32_e32 v139, v139
	v_add_f32_e32 v160, 1.0, v160
	v_add_f32_e32 v161, 1.0, v161
	v_add_f32_e32 v162, 1.0, v162
	v_add_f32_e32 v139, 1.0, v139
	v_log_f32_e32 v160, v160
	v_log_f32_e32 v161, v161
	v_log_f32_e32 v162, v162
	v_log_f32_e32 v139, v139
	v_fma_f32 v110, v160, s5, v110
	v_fma_f32 v111, v161, s5, v111
	v_fma_f32 v112, v162, s5, v112
	v_fma_f32 v113, v139, s5, v113
	v_fma_f32 v110, v110, s4, v0
	v_fma_f32 v111, v111, s4, v0
	v_fma_f32 v112, v112, s4, v0
	v_fma_f32 v113, v113, s4, v0
	v_exp_f32_e32 v110, v110
	v_exp_f32_e32 v111, v111
	v_exp_f32_e32 v112, v112
	v_exp_f32_e32 v113, v113
	v_mul_f32_e32 v110, s4, v110
	v_mul_f32_e32 v111, s4, v111
	v_mul_f32_e32 v112, s4, v112
	v_mul_f32_e32 v113, s4, v113
	v_exp_f32_e32 v110, v110
	v_exp_f32_e32 v111, v111
	v_exp_f32_e32 v112, v112
	v_exp_f32_e32 v113, v113
	s_nop 1
	global_store_dwordx4 v[142:143], v[110:113], off
	v_add_f32_e32 v106, v106, v130
	v_add_f32_e32 v107, v107, v131
	v_add_f32_e32 v108, v108, v132
	v_add_f32_e32 v109, v109, v133
	v_mul_f32_e64 v160, |v106|, s4
	v_mul_f32_e64 v161, |v107|, s4
	v_mul_f32_e64 v162, |v108|, s4
	v_mul_f32_e64 v139, |v109|, s4
	v_max_f32_e64 v106, -v106, 0
	v_max_f32_e64 v107, -v107, 0
	v_max_f32_e64 v108, -v108, 0
	v_max_f32_e64 v109, -v109, 0
	v_exp_f32_e32 v160, v160
	v_exp_f32_e32 v161, v161
	v_exp_f32_e32 v162, v162
	v_exp_f32_e32 v139, v139
	v_add_f32_e32 v160, 1.0, v160
	v_add_f32_e32 v161, 1.0, v161
	v_add_f32_e32 v162, 1.0, v162
	v_add_f32_e32 v139, 1.0, v139
	v_log_f32_e32 v160, v160
	v_log_f32_e32 v161, v161
	v_log_f32_e32 v162, v162
	v_log_f32_e32 v139, v139
	v_fma_f32 v106, v160, s5, v106
	v_fma_f32 v107, v161, s5, v107
	v_fma_f32 v108, v162, s5, v108
	v_fma_f32 v109, v139, s5, v109
	v_fma_f32 v106, v106, s4, v0
	v_fma_f32 v107, v107, s4, v0
	v_fma_f32 v108, v108, s4, v0
	v_fma_f32 v109, v109, s4, v0
	v_exp_f32_e32 v106, v106
	v_exp_f32_e32 v107, v107
	v_exp_f32_e32 v108, v108
	v_exp_f32_e32 v109, v109
	v_mul_f32_e32 v106, s4, v106
	v_mul_f32_e32 v107, s4, v107
	v_mul_f32_e32 v108, s4, v108
	v_mul_f32_e32 v109, s4, v109
	v_exp_f32_e32 v106, v106
	v_exp_f32_e32 v107, v107
	v_exp_f32_e32 v108, v108
	v_exp_f32_e32 v109, v109
	s_nop 1
	global_store_dwordx4 v[142:143], v[106:109], off offset:16
	v_add_f32_e32 v46, v46, v30
	v_add_f32_e32 v47, v47, v31
	v_add_f32_e32 v48, v48, v32
	v_add_f32_e32 v49, v49, v33
	v_mul_f32_e64 v160, |v46|, s4
	v_mul_f32_e64 v161, |v47|, s4
	v_mul_f32_e64 v162, |v48|, s4
	v_mul_f32_e64 v139, |v49|, s4
	v_max_f32_e64 v46, -v46, 0
	v_max_f32_e64 v47, -v47, 0
	v_max_f32_e64 v48, -v48, 0
	v_max_f32_e64 v49, -v49, 0
	v_exp_f32_e32 v160, v160
	v_exp_f32_e32 v161, v161
	v_exp_f32_e32 v162, v162
	v_exp_f32_e32 v139, v139
	v_add_f32_e32 v160, 1.0, v160
	v_add_f32_e32 v161, 1.0, v161
	v_add_f32_e32 v162, 1.0, v162
	v_add_f32_e32 v139, 1.0, v139
	v_log_f32_e32 v160, v160
	v_log_f32_e32 v161, v161
	v_log_f32_e32 v162, v162
	v_log_f32_e32 v139, v139
	v_fma_f32 v46, v160, s5, v46
	v_fma_f32 v47, v161, s5, v47
	v_fma_f32 v48, v162, s5, v48
	v_fma_f32 v49, v139, s5, v49
	v_fma_f32 v46, v46, s4, v0
	v_fma_f32 v47, v47, s4, v0
	v_fma_f32 v48, v48, s4, v0
	v_fma_f32 v49, v49, s4, v0
	v_exp_f32_e32 v46, v46
	v_exp_f32_e32 v47, v47
	v_exp_f32_e32 v48, v48
	v_exp_f32_e32 v49, v49
	v_mul_f32_e32 v46, s4, v46
	v_mul_f32_e32 v47, s4, v47
	v_mul_f32_e32 v48, s4, v48
	v_mul_f32_e32 v49, s4, v49
	v_exp_f32_e32 v46, v46
	v_exp_f32_e32 v47, v47
	v_exp_f32_e32 v48, v48
	v_exp_f32_e32 v49, v49
	s_nop 1
	global_store_dwordx4 v[142:143], v[46:49], off offset:512
	v_add_f32_e32 v42, v42, v34
	v_add_f32_e32 v43, v43, v35
	v_add_f32_e32 v44, v44, v36
	v_add_f32_e32 v45, v45, v37
	v_mul_f32_e64 v160, |v42|, s4
	v_mul_f32_e64 v161, |v43|, s4
	v_mul_f32_e64 v162, |v44|, s4
	v_mul_f32_e64 v139, |v45|, s4
	v_max_f32_e64 v42, -v42, 0
	v_max_f32_e64 v43, -v43, 0
	v_max_f32_e64 v44, -v44, 0
	v_max_f32_e64 v45, -v45, 0
	v_exp_f32_e32 v160, v160
	v_exp_f32_e32 v161, v161
	v_exp_f32_e32 v162, v162
	v_exp_f32_e32 v139, v139
	v_add_f32_e32 v160, 1.0, v160
	v_add_f32_e32 v161, 1.0, v161
	v_add_f32_e32 v162, 1.0, v162
	v_add_f32_e32 v139, 1.0, v139
	v_log_f32_e32 v160, v160
	v_log_f32_e32 v161, v161
	v_log_f32_e32 v162, v162
	v_log_f32_e32 v139, v139
	v_fma_f32 v42, v160, s5, v42
	v_fma_f32 v43, v161, s5, v43
	v_fma_f32 v44, v162, s5, v44
	v_fma_f32 v45, v139, s5, v45
	v_fma_f32 v42, v42, s4, v0
	v_fma_f32 v43, v43, s4, v0
	v_fma_f32 v44, v44, s4, v0
	v_fma_f32 v45, v45, s4, v0
	v_exp_f32_e32 v42, v42
	v_exp_f32_e32 v43, v43
	v_exp_f32_e32 v44, v44
	v_exp_f32_e32 v45, v45
	v_mul_f32_e32 v42, s4, v42
	v_mul_f32_e32 v43, s4, v43
	v_mul_f32_e32 v44, s4, v44
	v_mul_f32_e32 v45, s4, v45
	v_exp_f32_e32 v42, v42
	v_exp_f32_e32 v43, v43
	v_exp_f32_e32 v44, v44
	v_exp_f32_e32 v45, v45
	s_nop 1
	global_store_dwordx4 v[142:143], v[42:45], off offset:528
; DI float softplusf_(float x) { return fmaxf(x, 0.f) + log1pf(__expf(-fabsf(x))); }
;   DI void operator()(const Acc8& acc, const pg8::Unit& u, int wr, int wc, int fr, int fq) const {
;     ...
;           for (int m = 0; m < 4; ++m) {
;             const size_t o = (size_t)EPI_ROWS(ai, m) * 256 + c8;
;             const f32x4 x0 = acc[ai][bj][m][0], x1 = acc[ai][bj][m][1];
;             float4 d0, d1;
;             d0.x = __expf(-__expf(-softplusf_(-(w0a.x + x0[0])) - 0.5f)); d0.y = __expf(-__expf(-softplusf_(-(w0a.y + x0[1])) - 0.5f));
;             d0.z = __expf(-__expf(-softplusf_(-(w0a.z + x0[2])) - 0.5f)); d0.w = __expf(-__expf(-softplusf_(-(w0a.w + x0[3])) - 0.5f));
;             d1.x = __expf(-__expf(-softplusf_(-(w0b.x + x1[0])) - 0.5f)); d1.y = __expf(-__expf(-softplusf_(-(w0b.y + x1[1])) - 0.5f));
;             d1.z = __expf(-__expf(-softplusf_(-(w0b.z + x1[2])) - 0.5f)); d1.w = __expf(-__expf(-softplusf_(-(w0b.w + x1[3])) - 0.5f));
;             *(float4*)(sW + o) = d0; *(float4*)(sW + o + 4) = d1;
;             asm volatile("" ::: "memory"); __builtin_amdgcn_sched_barrier(0);
;           }
	v_lshlrev_b64 v[144:145], 10, v[154:155]
	v_lshl_add_u64 v[144:145], s[2:3], 0, v[144:145]
	v_lshl_add_u64 v[144:145], v[144:145], 0, v[146:147]
	v_add_f32_e32 v102, v102, v134
	v_add_f32_e32 v103, v103, v135
	v_add_f32_e32 v104, v104, v136
	v_add_f32_e32 v105, v105, v137
	v_mul_f32_e64 v160, |v102|, s4
	v_mul_f32_e64 v161, |v103|, s4
	v_mul_f32_e64 v162, |v104|, s4
	v_mul_f32_e64 v139, |v105|, s4
	v_max_f32_e64 v102, -v102, 0
	v_max_f32_e64 v103, -v103, 0
	v_max_f32_e64 v104, -v104, 0
	v_max_f32_e64 v105, -v105, 0
	v_exp_f32_e32 v160, v160
	v_exp_f32_e32 v161, v161
	v_exp_f32_e32 v162, v162
	v_exp_f32_e32 v139, v139
	v_add_f32_e32 v160, 1.0, v160
	v_add_f32_e32 v161, 1.0, v161
	v_add_f32_e32 v162, 1.0, v162
	v_add_f32_e32 v139, 1.0, v139
	v_log_f32_e32 v160, v160
	v_log_f32_e32 v161, v161
	v_log_f32_e32 v162, v162
	v_log_f32_e32 v139, v139
	v_fma_f32 v102, v160, s5, v102
	v_fma_f32 v103, v161, s5, v103
	v_fma_f32 v104, v162, s5, v104
	v_fma_f32 v105, v139, s5, v105
	v_fma_f32 v102, v102, s4, v0
	v_fma_f32 v103, v103, s4, v0
	v_fma_f32 v104, v104, s4, v0
	v_fma_f32 v105, v105, s4, v0
	v_exp_f32_e32 v102, v102
	v_exp_f32_e32 v103, v103
	v_exp_f32_e32 v104, v104
	v_exp_f32_e32 v105, v105
	v_mul_f32_e32 v102, s4, v102
	v_mul_f32_e32 v103, s4, v103
	v_mul_f32_e32 v104, s4, v104
	v_mul_f32_e32 v105, s4, v105
	v_exp_f32_e32 v102, v102
	v_exp_f32_e32 v103, v103
	v_exp_f32_e32 v104, v104
	v_exp_f32_e32 v105, v105
	s_nop 1
	global_store_dwordx4 v[144:145], v[102:105], off
	v_add_f32_e32 v98, v98, v130
	v_add_f32_e32 v99, v99, v131
	v_add_f32_e32 v100, v100, v132
	v_add_f32_e32 v101, v101, v133
	v_mul_f32_e64 v160, |v98|, s4
	v_mul_f32_e64 v161, |v99|, s4
	v_mul_f32_e64 v162, |v100|, s4
	v_mul_f32_e64 v139, |v101|, s4
	v_max_f32_e64 v98, -v98, 0
	v_max_f32_e64 v99, -v99, 0
	v_max_f32_e64 v100, -v100, 0
	v_max_f32_e64 v101, -v101, 0
	v_exp_f32_e32 v160, v160
	v_exp_f32_e32 v161, v161
	v_exp_f32_e32 v162, v162
	v_exp_f32_e32 v139, v139
	v_add_f32_e32 v160, 1.0, v160
	v_add_f32_e32 v161, 1.0, v161
	v_add_f32_e32 v162, 1.0, v162
	v_add_f32_e32 v139, 1.0, v139
	v_log_f32_e32 v160, v160
	v_log_f32_e32 v161, v161
	v_log_f32_e32 v162, v162
	v_log_f32_e32 v139, v139
	v_fma_f32 v98, v160, s5, v98
	v_fma_f32 v99, v161, s5, v99
	v_fma_f32 v100, v162, s5, v100
	v_fma_f32 v101, v139, s5, v101
	v_fma_f32 v98, v98, s4, v0
	v_fma_f32 v99, v99, s4, v0
	v_fma_f32 v100, v100, s4, v0
	v_fma_f32 v101, v101, s4, v0
	v_exp_f32_e32 v98, v98
	v_exp_f32_e32 v99, v99
	v_exp_f32_e32 v100, v100
	v_exp_f32_e32 v101, v101
	v_mul_f32_e32 v98, s4, v98
	v_mul_f32_e32 v99, s4, v99
	v_mul_f32_e32 v100, s4, v100
	v_mul_f32_e32 v101, s4, v101
	v_exp_f32_e32 v98, v98
	v_exp_f32_e32 v99, v99
	v_exp_f32_e32 v100, v100
	v_exp_f32_e32 v101, v101
	s_nop 1
	global_store_dwordx4 v[144:145], v[98:101], off offset:16
	v_add_f32_e32 v38, v38, v30
	v_add_f32_e32 v39, v39, v31
	v_add_f32_e32 v40, v40, v32
	v_add_f32_e32 v41, v41, v33
	v_mul_f32_e64 v160, |v38|, s4
	v_mul_f32_e64 v161, |v39|, s4
	v_mul_f32_e64 v162, |v40|, s4
	v_mul_f32_e64 v139, |v41|, s4
	v_max_f32_e64 v38, -v38, 0
	v_max_f32_e64 v39, -v39, 0
	v_max_f32_e64 v40, -v40, 0
	v_max_f32_e64 v41, -v41, 0
	v_exp_f32_e32 v160, v160
	v_exp_f32_e32 v161, v161
	v_exp_f32_e32 v162, v162
	v_exp_f32_e32 v139, v139
	v_add_f32_e32 v160, 1.0, v160
	v_add_f32_e32 v161, 1.0, v161
	v_add_f32_e32 v162, 1.0, v162
	v_add_f32_e32 v139, 1.0, v139
	v_log_f32_e32 v160, v160
	v_log_f32_e32 v161, v161
	v_log_f32_e32 v162, v162
	v_log_f32_e32 v139, v139
	v_fma_f32 v38, v160, s5, v38
	v_fma_f32 v39, v161, s5, v39
	v_fma_f32 v40, v162, s5, v40
	v_fma_f32 v41, v139, s5, v41
	v_fma_f32 v38, v38, s4, v0
	v_fma_f32 v39, v39, s4, v0
	v_fma_f32 v40, v40, s4, v0
	v_fma_f32 v41, v41, s4, v0
	v_exp_f32_e32 v38, v38
	v_exp_f32_e32 v39, v39
	v_exp_f32_e32 v40, v40
	v_exp_f32_e32 v41, v41
	v_mul_f32_e32 v38, s4, v38
	v_mul_f32_e32 v39, s4, v39
	v_mul_f32_e32 v40, s4, v40
	v_mul_f32_e32 v41, s4, v41
	v_exp_f32_e32 v38, v38
	v_exp_f32_e32 v39, v39
	v_exp_f32_e32 v40, v40
	v_exp_f32_e32 v41, v41
	s_nop 1
	global_store_dwordx4 v[144:145], v[38:41], off offset:512
	v_add_f32_e32 v184, v184, v34
	v_add_f32_e32 v185, v185, v35
	v_add_f32_e32 v186, v186, v36
	v_add_f32_e32 v187, v187, v37
	v_mul_f32_e64 v160, |v184|, s4
	v_mul_f32_e64 v161, |v185|, s4
	v_mul_f32_e64 v162, |v186|, s4
	v_mul_f32_e64 v139, |v187|, s4
	v_max_f32_e64 v184, -v184, 0
	v_max_f32_e64 v185, -v185, 0
	v_max_f32_e64 v186, -v186, 0
	v_max_f32_e64 v187, -v187, 0
	v_exp_f32_e32 v160, v160
	v_exp_f32_e32 v161, v161
	v_exp_f32_e32 v162, v162
	v_exp_f32_e32 v139, v139
	v_add_f32_e32 v160, 1.0, v160
	v_add_f32_e32 v161, 1.0, v161
	v_add_f32_e32 v162, 1.0, v162
	v_add_f32_e32 v139, 1.0, v139
	v_log_f32_e32 v160, v160
	v_log_f32_e32 v161, v161
	v_log_f32_e32 v162, v162
	v_log_f32_e32 v139, v139
	v_fma_f32 v184, v160, s5, v184
	v_fma_f32 v185, v161, s5, v185
	v_fma_f32 v186, v162, s5, v186
	v_fma_f32 v187, v139, s5, v187
	v_fma_f32 v184, v184, s4, v0
	v_fma_f32 v185, v185, s4, v0
	v_fma_f32 v186, v186, s4, v0
	v_fma_f32 v187, v187, s4, v0
	v_exp_f32_e32 v184, v184
	v_exp_f32_e32 v185, v185
	v_exp_f32_e32 v186, v186
	v_exp_f32_e32 v187, v187
	v_mul_f32_e32 v184, s4, v184
	v_mul_f32_e32 v185, s4, v185
	v_mul_f32_e32 v186, s4, v186
	v_mul_f32_e32 v187, s4, v187
	v_exp_f32_e32 v184, v184
	v_exp_f32_e32 v185, v185
	v_exp_f32_e32 v186, v186
	v_exp_f32_e32 v187, v187
	s_nop 1
	global_store_dwordx4 v[144:145], v[184:187], off offset:528
	v_lshlrev_b64 v[142:143], 10, v[152:153]
	v_lshl_add_u64 v[142:143], s[2:3], 0, v[142:143]
	v_lshl_add_u64 v[142:143], v[142:143], 0, v[146:147]
	v_add_f32_e32 v94, v94, v134
; DI float softplusf_(float x) { return fmaxf(x, 0.f) + log1pf(__expf(-fabsf(x))); }
;   DI void operator()(const Acc8& acc, const pg8::Unit& u, int wr, int wc, int fr, int fq) const {
;     ...
;           for (int m = 0; m < 4; ++m) {
;             const size_t o = (size_t)EPI_ROWS(ai, m) * 256 + c8;
;             const f32x4 x0 = acc[ai][bj][m][0], x1 = acc[ai][bj][m][1];
;             float4 d0, d1;
;             d0.x = __expf(-__expf(-softplusf_(-(w0a.x + x0[0])) - 0.5f)); d0.y = __expf(-__expf(-softplusf_(-(w0a.y + x0[1])) - 0.5f));
;             d0.z = __expf(-__expf(-softplusf_(-(w0a.z + x0[2])) - 0.5f)); d0.w = __expf(-__expf(-softplusf_(-(w0a.w + x0[3])) - 0.5f));
;             d1.x = __expf(-__expf(-softplusf_(-(w0b.x + x1[0])) - 0.5f)); d1.y = __expf(-__expf(-softplusf_(-(w0b.y + x1[1])) - 0.5f));
;             d1.z = __expf(-__expf(-softplusf_(-(w0b.z + x1[2])) - 0.5f)); d1.w = __expf(-__expf(-softplusf_(-(w0b.w + x1[3])) - 0.5f));
;             *(float4*)(sW + o) = d0; *(float4*)(sW + o + 4) = d1;
;             asm volatile("" ::: "memory"); __builtin_amdgcn_sched_barrier(0);
;           }
	v_add_f32_e32 v95, v95, v135
	v_add_f32_e32 v96, v96, v136
	v_add_f32_e32 v97, v97, v137
	v_mul_f32_e64 v160, |v94|, s4
	v_mul_f32_e64 v161, |v95|, s4
	v_mul_f32_e64 v162, |v96|, s4
	v_mul_f32_e64 v139, |v97|, s4
	v_max_f32_e64 v94, -v94, 0
	v_max_f32_e64 v95, -v95, 0
	v_max_f32_e64 v96, -v96, 0
	v_max_f32_e64 v97, -v97, 0
	v_exp_f32_e32 v160, v160
	v_exp_f32_e32 v161, v161
	v_exp_f32_e32 v162, v162
	v_exp_f32_e32 v139, v139
	v_add_f32_e32 v160, 1.0, v160
	v_add_f32_e32 v161, 1.0, v161
	v_add_f32_e32 v162, 1.0, v162
	v_add_f32_e32 v139, 1.0, v139
	v_log_f32_e32 v160, v160
	v_log_f32_e32 v161, v161
	v_log_f32_e32 v162, v162
	v_log_f32_e32 v139, v139
	v_fma_f32 v94, v160, s5, v94
	v_fma_f32 v95, v161, s5, v95
	v_fma_f32 v96, v162, s5, v96
	v_fma_f32 v97, v139, s5, v97
	v_fma_f32 v94, v94, s4, v0
	v_fma_f32 v95, v95, s4, v0
	v_fma_f32 v96, v96, s4, v0
	v_fma_f32 v97, v97, s4, v0
	v_exp_f32_e32 v94, v94
	v_exp_f32_e32 v95, v95
	v_exp_f32_e32 v96, v96
	v_exp_f32_e32 v97, v97
	v_mul_f32_e32 v94, s4, v94
	v_mul_f32_e32 v95, s4, v95
	v_mul_f32_e32 v96, s4, v96
	v_mul_f32_e32 v97, s4, v97
	v_exp_f32_e32 v94, v94
	v_exp_f32_e32 v95, v95
	v_exp_f32_e32 v96, v96
	v_exp_f32_e32 v97, v97
	s_nop 1
	global_store_dwordx4 v[142:143], v[94:97], off
	v_add_f32_e32 v90, v90, v130
	v_add_f32_e32 v91, v91, v131
	v_add_f32_e32 v92, v92, v132
	v_add_f32_e32 v93, v93, v133
	v_mul_f32_e64 v160, |v90|, s4
	v_mul_f32_e64 v161, |v91|, s4
	v_mul_f32_e64 v162, |v92|, s4
	v_mul_f32_e64 v139, |v93|, s4
	v_max_f32_e64 v90, -v90, 0
	v_max_f32_e64 v91, -v91, 0
	v_max_f32_e64 v92, -v92, 0
	v_max_f32_e64 v93, -v93, 0
	v_exp_f32_e32 v160, v160
	v_exp_f32_e32 v161, v161
	v_exp_f32_e32 v162, v162
	v_exp_f32_e32 v139, v139
	v_add_f32_e32 v160, 1.0, v160
	v_add_f32_e32 v161, 1.0, v161
	v_add_f32_e32 v162, 1.0, v162
	v_add_f32_e32 v139, 1.0, v139
	v_log_f32_e32 v160, v160
	v_log_f32_e32 v161, v161
	v_log_f32_e32 v162, v162
	v_log_f32_e32 v139, v139
	v_fma_f32 v90, v160, s5, v90
	v_fma_f32 v91, v161, s5, v91
	v_fma_f32 v92, v162, s5, v92
	v_fma_f32 v93, v139, s5, v93
	v_fma_f32 v90, v90, s4, v0
	v_fma_f32 v91, v91, s4, v0
	v_fma_f32 v92, v92, s4, v0
	v_fma_f32 v93, v93, s4, v0
	v_exp_f32_e32 v90, v90
	v_exp_f32_e32 v91, v91
	v_exp_f32_e32 v92, v92
	v_exp_f32_e32 v93, v93
	v_mul_f32_e32 v90, s4, v90
	v_mul_f32_e32 v91, s4, v91
	v_mul_f32_e32 v92, s4, v92
	v_mul_f32_e32 v93, s4, v93
	v_exp_f32_e32 v90, v90
	v_exp_f32_e32 v91, v91
	v_exp_f32_e32 v92, v92
	v_exp_f32_e32 v93, v93
	s_nop 1
	global_store_dwordx4 v[142:143], v[90:93], off offset:16
	v_add_f32_e32 v6, v6, v30
	v_add_f32_e32 v7, v7, v31
	v_add_f32_e32 v8, v8, v32
	v_add_f32_e32 v9, v9, v33
	v_mul_f32_e64 v160, |v6|, s4
	v_mul_f32_e64 v161, |v7|, s4
	v_mul_f32_e64 v162, |v8|, s4
	v_mul_f32_e64 v139, |v9|, s4
	v_max_f32_e64 v6, -v6, 0
	v_max_f32_e64 v7, -v7, 0
	v_max_f32_e64 v8, -v8, 0
	v_max_f32_e64 v9, -v9, 0
	v_exp_f32_e32 v160, v160
	v_exp_f32_e32 v161, v161
	v_exp_f32_e32 v162, v162
	v_exp_f32_e32 v139, v139
	v_add_f32_e32 v160, 1.0, v160
	v_add_f32_e32 v161, 1.0, v161
	v_add_f32_e32 v162, 1.0, v162
	v_add_f32_e32 v139, 1.0, v139
	v_log_f32_e32 v160, v160
	v_log_f32_e32 v161, v161
	v_log_f32_e32 v162, v162
	v_log_f32_e32 v139, v139
	v_fma_f32 v6, v160, s5, v6
	v_fma_f32 v7, v161, s5, v7
	v_fma_f32 v8, v162, s5, v8
	v_fma_f32 v9, v139, s5, v9
	v_fma_f32 v6, v6, s4, v0
	v_fma_f32 v7, v7, s4, v0
	v_fma_f32 v8, v8, s4, v0
	v_fma_f32 v9, v9, s4, v0
	v_exp_f32_e32 v6, v6
	v_exp_f32_e32 v7, v7
	v_exp_f32_e32 v8, v8
	v_exp_f32_e32 v9, v9
	v_mul_f32_e32 v6, s4, v6
	v_mul_f32_e32 v7, s4, v7
	v_mul_f32_e32 v8, s4, v8
	v_mul_f32_e32 v9, s4, v9
	v_exp_f32_e32 v6, v6
	v_exp_f32_e32 v7, v7
	v_exp_f32_e32 v8, v8
	v_exp_f32_e32 v9, v9
	s_nop 1
	global_store_dwordx4 v[142:143], v[6:9], off offset:512
	v_add_f32_e32 v26, v26, v34
	v_add_f32_e32 v27, v27, v35
	v_add_f32_e32 v28, v28, v36
	v_add_f32_e32 v29, v29, v37
	v_mul_f32_e64 v160, |v26|, s4
	v_mul_f32_e64 v161, |v27|, s4
	v_mul_f32_e64 v162, |v28|, s4
	v_mul_f32_e64 v139, |v29|, s4
	v_max_f32_e64 v26, -v26, 0
	v_max_f32_e64 v27, -v27, 0
	v_max_f32_e64 v28, -v28, 0
	v_max_f32_e64 v29, -v29, 0
	v_exp_f32_e32 v160, v160
	v_exp_f32_e32 v161, v161
	v_exp_f32_e32 v162, v162
	v_exp_f32_e32 v139, v139
	v_add_f32_e32 v160, 1.0, v160
	v_add_f32_e32 v161, 1.0, v161
	v_add_f32_e32 v162, 1.0, v162
	v_add_f32_e32 v139, 1.0, v139
	v_log_f32_e32 v160, v160
	v_log_f32_e32 v161, v161
	v_log_f32_e32 v162, v162
	v_log_f32_e32 v139, v139
	v_fma_f32 v26, v160, s5, v26
	v_fma_f32 v27, v161, s5, v27
	v_fma_f32 v28, v162, s5, v28
	v_fma_f32 v29, v139, s5, v29
	v_fma_f32 v26, v26, s4, v0
	v_fma_f32 v27, v27, s4, v0
	v_fma_f32 v28, v28, s4, v0
	v_fma_f32 v29, v29, s4, v0
	v_exp_f32_e32 v26, v26
	v_exp_f32_e32 v27, v27
	v_exp_f32_e32 v28, v28
	v_exp_f32_e32 v29, v29
	v_mul_f32_e32 v26, s4, v26
	v_mul_f32_e32 v27, s4, v27
	v_mul_f32_e32 v28, s4, v28
	v_mul_f32_e32 v29, s4, v29
	v_exp_f32_e32 v26, v26
	v_exp_f32_e32 v27, v27
	v_exp_f32_e32 v28, v28
	v_exp_f32_e32 v29, v29
	s_nop 1
	global_store_dwordx4 v[142:143], v[26:29], off offset:528
	v_lshlrev_b64 v[144:145], 10, v[150:151]
	v_lshl_add_u64 v[144:145], s[2:3], 0, v[144:145]
	v_lshl_add_u64 v[144:145], v[144:145], 0, v[146:147]
	v_add_f32_e32 v86, v86, v134
	v_add_f32_e32 v87, v87, v135
	v_add_f32_e32 v88, v88, v136
	v_add_f32_e32 v89, v89, v137
	v_mul_f32_e64 v160, |v86|, s4
	v_mul_f32_e64 v161, |v87|, s4
	v_mul_f32_e64 v162, |v88|, s4
	v_mul_f32_e64 v139, |v89|, s4
	v_max_f32_e64 v86, -v86, 0
	v_max_f32_e64 v87, -v87, 0
	v_max_f32_e64 v88, -v88, 0
	v_max_f32_e64 v89, -v89, 0
	v_exp_f32_e32 v160, v160
	v_exp_f32_e32 v161, v161
	v_exp_f32_e32 v162, v162
; DI float softplusf_(float x) { return fmaxf(x, 0.f) + log1pf(__expf(-fabsf(x))); }
;   DI void operator()(const Acc8& acc, const pg8::Unit& u, int wr, int wc, int fr, int fq) const {
;     ...
;           for (int m = 0; m < 4; ++m) {
;             const size_t o = (size_t)EPI_ROWS(ai, m) * 256 + c8;
;             const f32x4 x0 = acc[ai][bj][m][0], x1 = acc[ai][bj][m][1];
;             float4 d0, d1;
;             d0.x = __expf(-__expf(-softplusf_(-(w0a.x + x0[0])) - 0.5f)); d0.y = __expf(-__expf(-softplusf_(-(w0a.y + x0[1])) - 0.5f));
;             d0.z = __expf(-__expf(-softplusf_(-(w0a.z + x0[2])) - 0.5f)); d0.w = __expf(-__expf(-softplusf_(-(w0a.w + x0[3])) - 0.5f));
;             d1.x = __expf(-__expf(-softplusf_(-(w0b.x + x1[0])) - 0.5f)); d1.y = __expf(-__expf(-softplusf_(-(w0b.y + x1[1])) - 0.5f));
;             d1.z = __expf(-__expf(-softplusf_(-(w0b.z + x1[2])) - 0.5f)); d1.w = __expf(-__expf(-softplusf_(-(w0b.w + x1[3])) - 0.5f));
;             *(float4*)(sW + o) = d0; *(float4*)(sW + o + 4) = d1;
;             asm volatile("" ::: "memory"); __builtin_amdgcn_sched_barrier(0);
;           }
	v_exp_f32_e32 v139, v139
	v_add_f32_e32 v160, 1.0, v160
	v_add_f32_e32 v161, 1.0, v161
	v_add_f32_e32 v162, 1.0, v162
	v_add_f32_e32 v139, 1.0, v139
	v_log_f32_e32 v160, v160
	v_log_f32_e32 v161, v161
	v_log_f32_e32 v162, v162
	v_log_f32_e32 v139, v139
	v_fma_f32 v86, v160, s5, v86
	v_fma_f32 v87, v161, s5, v87
	v_fma_f32 v88, v162, s5, v88
	v_fma_f32 v89, v139, s5, v89
	v_fma_f32 v86, v86, s4, v0
	v_fma_f32 v87, v87, s4, v0
	v_fma_f32 v88, v88, s4, v0
	v_fma_f32 v89, v89, s4, v0
	v_exp_f32_e32 v86, v86
	v_exp_f32_e32 v87, v87
	v_exp_f32_e32 v88, v88
	v_exp_f32_e32 v89, v89
	v_mul_f32_e32 v86, s4, v86
	v_mul_f32_e32 v87, s4, v87
	v_mul_f32_e32 v88, s4, v88
	v_mul_f32_e32 v89, s4, v89
	v_exp_f32_e32 v86, v86
	v_exp_f32_e32 v87, v87
	v_exp_f32_e32 v88, v88
	v_exp_f32_e32 v89, v89
	s_nop 1
	global_store_dwordx4 v[144:145], v[86:89], off
	v_add_f32_e32 v82, v82, v130
	v_add_f32_e32 v83, v83, v131
	v_add_f32_e32 v84, v84, v132
	v_add_f32_e32 v85, v85, v133
	v_mul_f32_e64 v160, |v82|, s4
	v_mul_f32_e64 v161, |v83|, s4
	v_mul_f32_e64 v162, |v84|, s4
	v_mul_f32_e64 v139, |v85|, s4
	v_max_f32_e64 v82, -v82, 0
	v_max_f32_e64 v83, -v83, 0
	v_max_f32_e64 v84, -v84, 0
	v_max_f32_e64 v85, -v85, 0
	v_exp_f32_e32 v160, v160
	v_exp_f32_e32 v161, v161
	v_exp_f32_e32 v162, v162
	v_exp_f32_e32 v139, v139
	v_add_f32_e32 v160, 1.0, v160
	v_add_f32_e32 v161, 1.0, v161
	v_add_f32_e32 v162, 1.0, v162
	v_add_f32_e32 v139, 1.0, v139
	v_log_f32_e32 v160, v160
	v_log_f32_e32 v161, v161
	v_log_f32_e32 v162, v162
	v_log_f32_e32 v139, v139
	v_fma_f32 v82, v160, s5, v82
	v_fma_f32 v83, v161, s5, v83
	v_fma_f32 v84, v162, s5, v84
	v_fma_f32 v85, v139, s5, v85
	v_fma_f32 v82, v82, s4, v0
	v_fma_f32 v83, v83, s4, v0
	v_fma_f32 v84, v84, s4, v0
	v_fma_f32 v85, v85, s4, v0
	v_exp_f32_e32 v82, v82
	v_exp_f32_e32 v83, v83
	v_exp_f32_e32 v84, v84
	v_exp_f32_e32 v85, v85
	v_mul_f32_e32 v82, s4, v82
	v_mul_f32_e32 v83, s4, v83
	v_mul_f32_e32 v84, s4, v84
	v_mul_f32_e32 v85, s4, v85
	v_exp_f32_e32 v82, v82
	v_exp_f32_e32 v83, v83
	v_exp_f32_e32 v84, v84
	v_exp_f32_e32 v85, v85
	s_nop 1
	global_store_dwordx4 v[144:145], v[82:85], off offset:16
	v_add_f32_e32 v22, v22, v30
	v_add_f32_e32 v23, v23, v31
	v_add_f32_e32 v24, v24, v32
	v_add_f32_e32 v25, v25, v33
	v_mul_f32_e64 v160, |v22|, s4
	v_mul_f32_e64 v161, |v23|, s4
	v_mul_f32_e64 v162, |v24|, s4
	v_mul_f32_e64 v139, |v25|, s4
	v_max_f32_e64 v22, -v22, 0
	v_max_f32_e64 v23, -v23, 0
	v_max_f32_e64 v24, -v24, 0
	v_max_f32_e64 v25, -v25, 0
	v_exp_f32_e32 v160, v160
	v_exp_f32_e32 v161, v161
	v_exp_f32_e32 v162, v162
	v_exp_f32_e32 v139, v139
	v_add_f32_e32 v160, 1.0, v160
	v_add_f32_e32 v161, 1.0, v161
	v_add_f32_e32 v162, 1.0, v162
	v_add_f32_e32 v139, 1.0, v139
	v_log_f32_e32 v160, v160
	v_log_f32_e32 v161, v161
	v_log_f32_e32 v162, v162
	v_log_f32_e32 v139, v139
	v_fma_f32 v22, v160, s5, v22
	v_fma_f32 v23, v161, s5, v23
	v_fma_f32 v24, v162, s5, v24
	v_fma_f32 v25, v139, s5, v25
	v_fma_f32 v22, v22, s4, v0
	v_fma_f32 v23, v23, s4, v0
	v_fma_f32 v24, v24, s4, v0
	v_fma_f32 v25, v25, s4, v0
	v_exp_f32_e32 v22, v22
	v_exp_f32_e32 v23, v23
	v_exp_f32_e32 v24, v24
	v_exp_f32_e32 v25, v25
	v_mul_f32_e32 v22, s4, v22
	v_mul_f32_e32 v23, s4, v23
	v_mul_f32_e32 v24, s4, v24
	v_mul_f32_e32 v25, s4, v25
	v_exp_f32_e32 v22, v22
	v_exp_f32_e32 v23, v23
	v_exp_f32_e32 v24, v24
	v_exp_f32_e32 v25, v25
	s_nop 1
	global_store_dwordx4 v[144:145], v[22:25], off offset:512
	v_add_f32_e32 v18, v18, v34
	v_add_f32_e32 v19, v19, v35
	v_add_f32_e32 v20, v20, v36
	v_add_f32_e32 v21, v21, v37
	v_mul_f32_e64 v160, |v18|, s4
	v_mul_f32_e64 v161, |v19|, s4
	v_mul_f32_e64 v162, |v20|, s4
	v_mul_f32_e64 v139, |v21|, s4
	v_max_f32_e64 v18, -v18, 0
	v_max_f32_e64 v19, -v19, 0
	v_max_f32_e64 v20, -v20, 0
	v_max_f32_e64 v21, -v21, 0
	v_exp_f32_e32 v160, v160
	v_exp_f32_e32 v161, v161
	v_exp_f32_e32 v162, v162
	v_exp_f32_e32 v139, v139
	v_add_f32_e32 v160, 1.0, v160
	v_add_f32_e32 v161, 1.0, v161
	v_add_f32_e32 v162, 1.0, v162
	v_add_f32_e32 v139, 1.0, v139
	v_log_f32_e32 v160, v160
	v_log_f32_e32 v161, v161
	v_log_f32_e32 v162, v162
	v_log_f32_e32 v139, v139
	v_fma_f32 v18, v160, s5, v18
	v_fma_f32 v19, v161, s5, v19
	v_fma_f32 v20, v162, s5, v20
	v_fma_f32 v21, v139, s5, v21
	v_fma_f32 v18, v18, s4, v0
	v_fma_f32 v19, v19, s4, v0
	v_fma_f32 v20, v20, s4, v0
	v_fma_f32 v21, v21, s4, v0
	v_exp_f32_e32 v18, v18
	v_exp_f32_e32 v19, v19
	v_exp_f32_e32 v20, v20
	v_exp_f32_e32 v21, v21
	v_mul_f32_e32 v18, s4, v18
	v_mul_f32_e32 v19, s4, v19
	v_mul_f32_e32 v20, s4, v20
	v_mul_f32_e32 v21, s4, v21
	v_exp_f32_e32 v18, v18
	v_exp_f32_e32 v19, v19
	v_exp_f32_e32 v20, v20
	v_exp_f32_e32 v21, v21
	s_nop 1
	global_store_dwordx4 v[144:145], v[18:21], off offset:528
	v_lshlrev_b64 v[142:143], 10, v[148:149]
	v_lshl_add_u64 v[142:143], s[2:3], 0, v[142:143]
	v_lshl_add_u64 v[142:143], v[142:143], 0, v[146:147]
	v_add_f32_e32 v78, v78, v134
	v_add_f32_e32 v79, v79, v135
	v_add_f32_e32 v80, v80, v136
	v_add_f32_e32 v81, v81, v137
	v_mul_f32_e64 v160, |v78|, s4
	v_mul_f32_e64 v161, |v79|, s4
	v_mul_f32_e64 v162, |v80|, s4
	v_mul_f32_e64 v139, |v81|, s4
	v_max_f32_e64 v78, -v78, 0
	v_max_f32_e64 v79, -v79, 0
	v_max_f32_e64 v80, -v80, 0
	v_max_f32_e64 v81, -v81, 0
	v_exp_f32_e32 v160, v160
	v_exp_f32_e32 v161, v161
	v_exp_f32_e32 v162, v162
	v_exp_f32_e32 v139, v139
	v_add_f32_e32 v160, 1.0, v160
	v_add_f32_e32 v161, 1.0, v161
	v_add_f32_e32 v162, 1.0, v162
	v_add_f32_e32 v139, 1.0, v139
	v_log_f32_e32 v160, v160
	v_log_f32_e32 v161, v161
	v_log_f32_e32 v162, v162
	v_log_f32_e32 v139, v139
	v_fma_f32 v78, v160, s5, v78
	v_fma_f32 v79, v161, s5, v79
	v_fma_f32 v80, v162, s5, v80
; DI float softplusf_(float x) { return fmaxf(x, 0.f) + log1pf(__expf(-fabsf(x))); }
;   DI void operator()(const Acc8& acc, const pg8::Unit& u, int wr, int wc, int fr, int fq) const {
;     ...
;           for (int m = 0; m < 4; ++m) {
;             const size_t o = (size_t)EPI_ROWS(ai, m) * 256 + c8;
;             const f32x4 x0 = acc[ai][bj][m][0], x1 = acc[ai][bj][m][1];
;             float4 d0, d1;
;             d0.x = __expf(-__expf(-softplusf_(-(w0a.x + x0[0])) - 0.5f)); d0.y = __expf(-__expf(-softplusf_(-(w0a.y + x0[1])) - 0.5f));
;             d0.z = __expf(-__expf(-softplusf_(-(w0a.z + x0[2])) - 0.5f)); d0.w = __expf(-__expf(-softplusf_(-(w0a.w + x0[3])) - 0.5f));
;             d1.x = __expf(-__expf(-softplusf_(-(w0b.x + x1[0])) - 0.5f)); d1.y = __expf(-__expf(-softplusf_(-(w0b.y + x1[1])) - 0.5f));
;             d1.z = __expf(-__expf(-softplusf_(-(w0b.z + x1[2])) - 0.5f)); d1.w = __expf(-__expf(-softplusf_(-(w0b.w + x1[3])) - 0.5f));
;             *(float4*)(sW + o) = d0; *(float4*)(sW + o + 4) = d1;
;             asm volatile("" ::: "memory"); __builtin_amdgcn_sched_barrier(0);
;           }
	v_fma_f32 v81, v139, s5, v81
	v_fma_f32 v78, v78, s4, v0
	v_fma_f32 v79, v79, s4, v0
	v_fma_f32 v80, v80, s4, v0
	v_fma_f32 v81, v81, s4, v0
	v_exp_f32_e32 v78, v78
	v_exp_f32_e32 v79, v79
	v_exp_f32_e32 v80, v80
	v_exp_f32_e32 v81, v81
	v_mul_f32_e32 v78, s4, v78
	v_mul_f32_e32 v79, s4, v79
	v_mul_f32_e32 v80, s4, v80
	v_mul_f32_e32 v81, s4, v81
	v_exp_f32_e32 v78, v78
	v_exp_f32_e32 v79, v79
	v_exp_f32_e32 v80, v80
	v_exp_f32_e32 v81, v81
	s_nop 1
	global_store_dwordx4 v[142:143], v[78:81], off
	v_add_f32_e32 v74, v74, v130
	v_add_f32_e32 v75, v75, v131
	v_add_f32_e32 v76, v76, v132
	v_add_f32_e32 v77, v77, v133
	v_mul_f32_e64 v160, |v74|, s4
	v_mul_f32_e64 v161, |v75|, s4
	v_mul_f32_e64 v162, |v76|, s4
	v_mul_f32_e64 v139, |v77|, s4
	v_max_f32_e64 v74, -v74, 0
	v_max_f32_e64 v75, -v75, 0
	v_max_f32_e64 v76, -v76, 0
	v_max_f32_e64 v77, -v77, 0
	v_exp_f32_e32 v160, v160
	v_exp_f32_e32 v161, v161
	v_exp_f32_e32 v162, v162
	v_exp_f32_e32 v139, v139
	v_add_f32_e32 v160, 1.0, v160
	v_add_f32_e32 v161, 1.0, v161
	v_add_f32_e32 v162, 1.0, v162
	v_add_f32_e32 v139, 1.0, v139
	v_log_f32_e32 v160, v160
	v_log_f32_e32 v161, v161
	v_log_f32_e32 v162, v162
	v_log_f32_e32 v139, v139
	v_fma_f32 v74, v160, s5, v74
	v_fma_f32 v75, v161, s5, v75
	v_fma_f32 v76, v162, s5, v76
	v_fma_f32 v77, v139, s5, v77
	v_fma_f32 v74, v74, s4, v0
	v_fma_f32 v75, v75, s4, v0
	v_fma_f32 v76, v76, s4, v0
	v_fma_f32 v77, v77, s4, v0
	v_exp_f32_e32 v74, v74
	v_exp_f32_e32 v75, v75
	v_exp_f32_e32 v76, v76
	v_exp_f32_e32 v77, v77
	v_mul_f32_e32 v74, s4, v74
	v_mul_f32_e32 v75, s4, v75
	v_mul_f32_e32 v76, s4, v76
	v_mul_f32_e32 v77, s4, v77
	v_exp_f32_e32 v74, v74
	v_exp_f32_e32 v75, v75
	v_exp_f32_e32 v76, v76
	v_exp_f32_e32 v77, v77
	s_nop 1
	global_store_dwordx4 v[142:143], v[74:77], off offset:16
	v_add_f32_e32 v14, v14, v30
	v_add_f32_e32 v15, v15, v31
	v_add_f32_e32 v16, v16, v32
	v_add_f32_e32 v17, v17, v33
	v_mul_f32_e64 v160, |v14|, s4
	v_mul_f32_e64 v161, |v15|, s4
	v_mul_f32_e64 v162, |v16|, s4
	v_mul_f32_e64 v139, |v17|, s4
	v_max_f32_e64 v14, -v14, 0
	v_max_f32_e64 v15, -v15, 0
	v_max_f32_e64 v16, -v16, 0
	v_max_f32_e64 v17, -v17, 0
	v_exp_f32_e32 v160, v160
	v_exp_f32_e32 v161, v161
	v_exp_f32_e32 v162, v162
	v_exp_f32_e32 v139, v139
	v_add_f32_e32 v160, 1.0, v160
	v_add_f32_e32 v161, 1.0, v161
	v_add_f32_e32 v162, 1.0, v162
	v_add_f32_e32 v139, 1.0, v139
	v_log_f32_e32 v160, v160
	v_log_f32_e32 v161, v161
	v_log_f32_e32 v162, v162
	v_log_f32_e32 v139, v139
	v_fma_f32 v14, v160, s5, v14
	v_fma_f32 v15, v161, s5, v15
	v_fma_f32 v16, v162, s5, v16
	v_fma_f32 v17, v139, s5, v17
	v_fma_f32 v14, v14, s4, v0
	v_fma_f32 v15, v15, s4, v0
	v_fma_f32 v16, v16, s4, v0
	v_fma_f32 v17, v17, s4, v0
	v_exp_f32_e32 v14, v14
	v_exp_f32_e32 v15, v15
	v_exp_f32_e32 v16, v16
	v_exp_f32_e32 v17, v17
	v_mul_f32_e32 v14, s4, v14
	v_mul_f32_e32 v15, s4, v15
	v_mul_f32_e32 v16, s4, v16
	v_mul_f32_e32 v17, s4, v17
	v_exp_f32_e32 v14, v14
	v_exp_f32_e32 v15, v15
	v_exp_f32_e32 v16, v16
	v_exp_f32_e32 v17, v17
	s_nop 1
	global_store_dwordx4 v[142:143], v[14:17], off offset:512
	v_add_f32_e32 v10, v10, v34
	v_add_f32_e32 v11, v11, v35
	v_add_f32_e32 v12, v12, v36
	v_add_f32_e32 v13, v13, v37
	v_mul_f32_e64 v160, |v10|, s4
	v_mul_f32_e64 v161, |v11|, s4
	v_mul_f32_e64 v162, |v12|, s4
	v_mul_f32_e64 v139, |v13|, s4
	v_max_f32_e64 v10, -v10, 0
	v_max_f32_e64 v11, -v11, 0
	v_max_f32_e64 v12, -v12, 0
	v_max_f32_e64 v13, -v13, 0
	v_exp_f32_e32 v160, v160
	v_exp_f32_e32 v161, v161
	v_exp_f32_e32 v162, v162
	v_exp_f32_e32 v139, v139
	v_add_f32_e32 v160, 1.0, v160
	v_add_f32_e32 v161, 1.0, v161
	v_add_f32_e32 v162, 1.0, v162
	v_add_f32_e32 v139, 1.0, v139
	v_log_f32_e32 v160, v160
	v_log_f32_e32 v161, v161
	v_log_f32_e32 v162, v162
	v_log_f32_e32 v139, v139
	v_fma_f32 v10, v160, s5, v10
	v_fma_f32 v11, v161, s5, v11
	v_fma_f32 v12, v162, s5, v12
	v_fma_f32 v13, v139, s5, v13
	v_fma_f32 v10, v10, s4, v0
	v_fma_f32 v11, v11, s4, v0
	v_fma_f32 v12, v12, s4, v0
	v_fma_f32 v13, v13, s4, v0
	v_exp_f32_e32 v10, v10
	v_exp_f32_e32 v11, v11
	v_exp_f32_e32 v12, v12
	v_exp_f32_e32 v13, v13
	v_mul_f32_e32 v10, s4, v10
	v_mul_f32_e32 v11, s4, v11
	v_mul_f32_e32 v12, s4, v12
	v_mul_f32_e32 v13, s4, v13
	v_exp_f32_e32 v10, v10
	v_exp_f32_e32 v11, v11
	v_exp_f32_e32 v12, v12
	v_exp_f32_e32 v13, v13
	s_nop 1
	global_store_dwordx4 v[142:143], v[10:13], off offset:528
	v_lshlrev_b64 v[144:145], 10, v[140:141]
	v_lshl_add_u64 v[144:145], s[2:3], 0, v[144:145]
	v_lshl_add_u64 v[144:145], v[144:145], 0, v[146:147]
	v_add_f32_e32 v70, v70, v134
	v_add_f32_e32 v71, v71, v135
	v_add_f32_e32 v72, v72, v136
	v_add_f32_e32 v73, v73, v137
	v_mul_f32_e64 v160, |v70|, s4
	v_mul_f32_e64 v161, |v71|, s4
	v_mul_f32_e64 v162, |v72|, s4
	v_mul_f32_e64 v139, |v73|, s4
	v_max_f32_e64 v70, -v70, 0
	v_max_f32_e64 v71, -v71, 0
	v_max_f32_e64 v72, -v72, 0
; DI float softplusf_(float x) { return fmaxf(x, 0.f) + log1pf(__expf(-fabsf(x))); }
;   DI void operator()(const Acc8& acc, const pg8::Unit& u, int wr, int wc, int fr, int fq) const {
;     ...
;           for (int m = 0; m < 4; ++m) {
;             const size_t o = (size_t)EPI_ROWS(ai, m) * 256 + c8;
;             const f32x4 x0 = acc[ai][bj][m][0], x1 = acc[ai][bj][m][1];
;             float4 d0, d1;
;             d0.x = __expf(-__expf(-softplusf_(-(w0a.x + x0[0])) - 0.5f)); d0.y = __expf(-__expf(-softplusf_(-(w0a.y + x0[1])) - 0.5f));
;             d0.z = __expf(-__expf(-softplusf_(-(w0a.z + x0[2])) - 0.5f)); d0.w = __expf(-__expf(-softplusf_(-(w0a.w + x0[3])) - 0.5f));
;             d1.x = __expf(-__expf(-softplusf_(-(w0b.x + x1[0])) - 0.5f)); d1.y = __expf(-__expf(-softplusf_(-(w0b.y + x1[1])) - 0.5f));
;             d1.z = __expf(-__expf(-softplusf_(-(w0b.z + x1[2])) - 0.5f)); d1.w = __expf(-__expf(-softplusf_(-(w0b.w + x1[3])) - 0.5f));
;             *(float4*)(sW + o) = d0; *(float4*)(sW + o + 4) = d1;
;             asm volatile("" ::: "memory"); __builtin_amdgcn_sched_barrier(0);
;           }
	v_max_f32_e64 v73, -v73, 0
	v_exp_f32_e32 v160, v160
	v_exp_f32_e32 v161, v161
	v_exp_f32_e32 v162, v162
	v_exp_f32_e32 v139, v139
	v_add_f32_e32 v160, 1.0, v160
	v_add_f32_e32 v161, 1.0, v161
	v_add_f32_e32 v162, 1.0, v162
	v_add_f32_e32 v139, 1.0, v139
	v_log_f32_e32 v160, v160
	v_log_f32_e32 v161, v161
	v_log_f32_e32 v162, v162
	v_log_f32_e32 v139, v139
	v_fma_f32 v70, v160, s5, v70
	v_fma_f32 v71, v161, s5, v71
	v_fma_f32 v72, v162, s5, v72
	v_fma_f32 v73, v139, s5, v73
	v_fma_f32 v70, v70, s4, v0
	v_fma_f32 v71, v71, s4, v0
	v_fma_f32 v72, v72, s4, v0
	v_fma_f32 v73, v73, s4, v0
	v_exp_f32_e32 v70, v70
	v_exp_f32_e32 v71, v71
	v_exp_f32_e32 v72, v72
	v_exp_f32_e32 v73, v73
	v_mul_f32_e32 v70, s4, v70
	v_mul_f32_e32 v71, s4, v71
	v_mul_f32_e32 v72, s4, v72
	v_mul_f32_e32 v73, s4, v73
	v_exp_f32_e32 v70, v70
	v_exp_f32_e32 v71, v71
	v_exp_f32_e32 v72, v72
	v_exp_f32_e32 v73, v73
	s_nop 1
	global_store_dwordx4 v[144:145], v[70:73], off
	v_add_f32_e32 v66, v66, v130
	v_add_f32_e32 v67, v67, v131
	v_add_f32_e32 v68, v68, v132
	v_add_f32_e32 v69, v69, v133
	v_mul_f32_e64 v160, |v66|, s4
	v_mul_f32_e64 v161, |v67|, s4
	v_mul_f32_e64 v162, |v68|, s4
	v_mul_f32_e64 v139, |v69|, s4
	v_max_f32_e64 v66, -v66, 0
	v_max_f32_e64 v67, -v67, 0
	v_max_f32_e64 v68, -v68, 0
	v_max_f32_e64 v69, -v69, 0
	v_exp_f32_e32 v160, v160
	v_exp_f32_e32 v161, v161
	v_exp_f32_e32 v162, v162
	v_exp_f32_e32 v139, v139
	v_add_f32_e32 v160, 1.0, v160
	v_add_f32_e32 v161, 1.0, v161
	v_add_f32_e32 v162, 1.0, v162
	v_add_f32_e32 v139, 1.0, v139
	v_log_f32_e32 v160, v160
	v_log_f32_e32 v161, v161
	v_log_f32_e32 v162, v162
	v_log_f32_e32 v139, v139
	v_fma_f32 v66, v160, s5, v66
	v_fma_f32 v67, v161, s5, v67
	v_fma_f32 v68, v162, s5, v68
	v_fma_f32 v69, v139, s5, v69
	v_fma_f32 v66, v66, s4, v0
	v_fma_f32 v67, v67, s4, v0
	v_fma_f32 v68, v68, s4, v0
	v_fma_f32 v69, v69, s4, v0
	v_exp_f32_e32 v66, v66
	v_exp_f32_e32 v67, v67
	v_exp_f32_e32 v68, v68
	v_exp_f32_e32 v69, v69
	v_mul_f32_e32 v66, s4, v66
	v_mul_f32_e32 v67, s4, v67
	v_mul_f32_e32 v68, s4, v68
	v_mul_f32_e32 v69, s4, v69
	v_exp_f32_e32 v66, v66
	v_exp_f32_e32 v67, v67
	v_exp_f32_e32 v68, v68
	v_exp_f32_e32 v69, v69
	s_nop 1
	global_store_dwordx4 v[144:145], v[66:69], off offset:16
	v_add_f32_e32 v222, v222, v30
	v_add_f32_e32 v223, v223, v31
	v_add_f32_e32 v224, v224, v32
	v_add_f32_e32 v225, v225, v33
	v_mul_f32_e64 v160, |v222|, s4
	v_mul_f32_e64 v161, |v223|, s4
	v_mul_f32_e64 v162, |v224|, s4
	v_mul_f32_e64 v139, |v225|, s4
	v_max_f32_e64 v222, -v222, 0
	v_max_f32_e64 v223, -v223, 0
	v_max_f32_e64 v224, -v224, 0
	v_max_f32_e64 v225, -v225, 0
	v_exp_f32_e32 v160, v160
	v_exp_f32_e32 v161, v161
	v_exp_f32_e32 v162, v162
	v_exp_f32_e32 v139, v139
	v_add_f32_e32 v160, 1.0, v160
	v_add_f32_e32 v161, 1.0, v161
	v_add_f32_e32 v162, 1.0, v162
	v_add_f32_e32 v139, 1.0, v139
	v_log_f32_e32 v160, v160
	v_log_f32_e32 v161, v161
	v_log_f32_e32 v162, v162
	v_log_f32_e32 v139, v139
	v_fma_f32 v222, v160, s5, v222
	v_fma_f32 v223, v161, s5, v223
	v_fma_f32 v224, v162, s5, v224
	v_fma_f32 v225, v139, s5, v225
	v_fma_f32 v222, v222, s4, v0
	v_fma_f32 v223, v223, s4, v0
	v_fma_f32 v224, v224, s4, v0
	v_fma_f32 v225, v225, s4, v0
	v_exp_f32_e32 v222, v222
	v_exp_f32_e32 v223, v223
	v_exp_f32_e32 v224, v224
	v_exp_f32_e32 v225, v225
	v_mul_f32_e32 v222, s4, v222
	v_mul_f32_e32 v223, s4, v223
	v_mul_f32_e32 v224, s4, v224
	v_mul_f32_e32 v225, s4, v225
	v_exp_f32_e32 v222, v222
	v_exp_f32_e32 v223, v223
	v_exp_f32_e32 v224, v224
	v_exp_f32_e32 v225, v225
	s_nop 1
	global_store_dwordx4 v[144:145], v[222:225], off offset:512
	v_add_f32_e32 v2, v2, v34
	v_add_f32_e32 v3, v3, v35
	v_add_f32_e32 v4, v4, v36
	v_add_f32_e32 v5, v5, v37
	v_mul_f32_e64 v160, |v2|, s4
	v_mul_f32_e64 v161, |v3|, s4
	v_mul_f32_e64 v162, |v4|, s4
	v_mul_f32_e64 v139, |v5|, s4
	v_max_f32_e64 v2, -v2, 0
	v_max_f32_e64 v3, -v3, 0
	v_max_f32_e64 v4, -v4, 0
	v_max_f32_e64 v5, -v5, 0
	v_exp_f32_e32 v160, v160
	v_exp_f32_e32 v161, v161
	v_exp_f32_e32 v162, v162
	v_exp_f32_e32 v139, v139
	v_add_f32_e32 v160, 1.0, v160
	v_add_f32_e32 v161, 1.0, v161
	v_add_f32_e32 v162, 1.0, v162
	v_add_f32_e32 v139, 1.0, v139
	v_log_f32_e32 v160, v160
	v_log_f32_e32 v161, v161
	v_log_f32_e32 v162, v162
	v_log_f32_e32 v139, v139
	v_fma_f32 v2, v160, s5, v2
	v_fma_f32 v3, v161, s5, v3
	v_fma_f32 v4, v162, s5, v4
	v_fma_f32 v5, v139, s5, v5
	v_fma_f32 v2, v2, s4, v0
	v_fma_f32 v3, v3, s4, v0
	v_fma_f32 v4, v4, s4, v0
	v_fma_f32 v5, v5, s4, v0
	v_exp_f32_e32 v2, v2
	v_exp_f32_e32 v3, v3
	v_exp_f32_e32 v4, v4
	v_exp_f32_e32 v5, v5
	v_mul_f32_e32 v2, s4, v2
	v_mul_f32_e32 v3, s4, v3
	v_mul_f32_e32 v4, s4, v4
	v_mul_f32_e32 v5, s4, v5
	v_exp_f32_e32 v2, v2
	v_exp_f32_e32 v3, v3
	v_exp_f32_e32 v4, v4
	v_exp_f32_e32 v5, v5
	s_nop 1
	global_store_dwordx4 v[144:145], v[2:5], off offset:528

; #define PG8_STAGE(bufoff, gbase, voff) do { _Pragma("unroll") for (int _i = 0; _i < 2; ++_i) \
;     __builtin_amdgcn_global_load_lds((const unsigned*)((const char*)(gbase) + (voff)[_i]), (LAS unsigned*)(lds + (bufoff) + ldsw + _i * 8192), 16, 0, 0); } while (0)
; #define PG8_LDA(dst, b, h) do { _Pragma("unroll") for (int m = 0; m < 4; ++m) _Pragma("unroll") for (int k = 0; k < 2; ++k) dst[m][k] = *(const LAS bf16x8*)(lds + PG8_SA(b, h) + aoff + m * 2048 + k * 1024); } while (0)
; #define PG8_LDB(dst, b, h) do { _Pragma("unroll") for (int n = 0; n < 2; ++n) _Pragma("unroll") for (int k = 0; k < 2; ++k) dst[n][k] = *(const LAS bf16x8*)(lds + PG8_SB(b, h) + boff + n * 2048 + k * 1024); } while (0)
; #define PG8_MMA(ai, bj, At, Bt) do { __builtin_amdgcn_s_setprio(1); _Pragma("unroll") for (int m = 0; m < 4; ++m) _Pragma("unroll") for (int n = 0; n < 2; ++n) _Pragma("unroll") for (int k = 0; k < 2; ++k) \
;     acc[ai][bj][m][n] = __builtin_amdgcn_mfma_f32_16x16x32_bf16(Bt[n][k], At[m][k], acc[ai][bj][m][n], 0, 0, 0); __builtin_amdgcn_s_setprio(0); } while (0)
; #define PG8_WAIT_V(n) asm volatile("s_waitcnt vmcnt(" #n ")" ::: "memory")
; #define PG8_WAIT_L(n) asm volatile("s_waitcnt lgkmcnt(" #n ")" ::: "memory")
; #define PG8_BAR __builtin_amdgcn_s_barrier()
; #define PG8_SCHED __builtin_amdgcn_sched_barrier(0)
; template <class Epi, class Sched>
; DI void gemm_phase(LAS unsigned char* lds, const Gemm g, const Sched& S, const Epi& E, int wid_k) {
;     ...
;       PG8_LDB(B0, 0, 0); PG8_SCHED; PG8_LDA(At, 0, 0); PG8_STAGE(PG8_SA(1, 1), a1 + hstepA, voffA);
;       PG8_WAIT_L(8); PG8_BAR; PG8_WAIT_L(0); PG8_MMA(0, 0, At, B0); PG8_BAR; PG8_SCHED;
;       PG8_LDB(B1, 0, 1); PG8_STAGE(PG8_SB(0, 0), b2, voffB);
;       PG8_BAR; PG8_WAIT_L(0); PG8_MMA(0, 1, At, B1); PG8_BAR;
;       PG8_LDA(At, 0, 1); PG8_STAGE(PG8_SA(0, 0), a2, voffA);
;       PG8_BAR; PG8_WAIT_L(0); PG8_MMA(1, 0, At, B0); PG8_BAR; PG8_SCHED;
;       PG8_STAGE(PG8_SB(0, 1), b2 + hstepB, voffB);
;       PG8_WAIT_V(6); PG8_BAR; PG8_MMA(1, 1, At, B1); PG8_BAR;
.LBB0_561:
	s_add_u32 s10, s8, 0xfffc0080
	s_addc_u32 s11, s9, -1
	s_add_i32 s67, 0, 0x10000
	v_add_u32_e32 v0, s67, v154
	ds_read_b128 v[142:145], v0
	ds_read_b128 v[146:149], v0 offset:1024
	ds_read_b128 v[156:159], v0 offset:2048
	ds_read_b128 v[160:163], v0 offset:3072
	s_cmp_eq_u32 s66, 12
	s_cselect_b32 s13, s5, s11
	s_cselect_b32 s12, s7, s10
	s_cselect_b32 s11, s39, s49
	s_cselect_b32 s10, s41, s48
	v_lshl_add_u64 v[150:151], s[8:9], 0, v[138:139]
	s_add_i32 m0, s85, 0xc000
	ds_read_b128 v[164:167], v155
	ds_read_b128 v[168:171], v155 offset:1024
	ds_read_b128 v[172:175], v155 offset:2048
	ds_read_b128 v[176:179], v155 offset:3072
	ds_read_b128 v[180:183], v155 offset:4096
	ds_read_b128 v[190:193], v155 offset:5120
	ds_read_b128 v[194:197], v155 offset:6144
	ds_read_b128 v[198:201], v155 offset:7168
	global_load_lds_dwordx4 v[150:151], off
	v_lshl_add_u64 v[150:151], s[8:9], 0, v[140:141]
	s_add_i32 m0, s85, 0xe000
	s_nop 0
	global_load_lds_dwordx4 v[150:151], off
	s_waitcnt lgkmcnt(8)
	s_barrier
	s_waitcnt lgkmcnt(0)
	s_setprio 1
	s_waitcnt lgkmcnt(0)
	v_mfma_f32_16x16x32_bf16 v[126:129], v[142:145], v[164:167], v[126:129]
	v_mfma_f32_16x16x32_bf16 v[122:125], v[156:159], v[164:167], v[122:125]
	v_mfma_f32_16x16x32_bf16 v[118:121], v[142:145], v[172:175], v[118:121]
	v_mfma_f32_16x16x32_bf16 v[114:117], v[156:159], v[172:175], v[114:117]
	v_mfma_f32_16x16x32_bf16 v[110:113], v[142:145], v[180:183], v[110:113]
	v_mfma_f32_16x16x32_bf16 v[106:109], v[156:159], v[180:183], v[106:109]
	v_mfma_f32_16x16x32_bf16 v[102:105], v[142:145], v[194:197], v[102:105]
	v_mfma_f32_16x16x32_bf16 v[98:101], v[156:159], v[194:197], v[98:101]
	v_mfma_f32_16x16x32_bf16 v[126:129], v[146:149], v[168:171], v[126:129]
	v_mfma_f32_16x16x32_bf16 v[122:125], v[160:163], v[168:171], v[122:125]
	v_mfma_f32_16x16x32_bf16 v[118:121], v[146:149], v[176:179], v[118:121]
	v_mfma_f32_16x16x32_bf16 v[114:117], v[160:163], v[176:179], v[114:117]
	v_mfma_f32_16x16x32_bf16 v[110:113], v[146:149], v[190:193], v[110:113]
	v_mfma_f32_16x16x32_bf16 v[106:109], v[160:163], v[190:193], v[106:109]
	v_mfma_f32_16x16x32_bf16 v[102:105], v[146:149], v[198:201], v[102:105]
	v_mfma_f32_16x16x32_bf16 v[98:101], v[160:163], v[198:201], v[98:101]
	s_setprio 0
	s_barrier
	s_add_i32 s70, 0, 0x14000
	s_add_i32 s67, s67, s31
	v_add_u32_e32 v0, s70, v154
	v_lshl_add_u64 v[150:151], s[10:11], 0, v[132:133]
	s_mov_b32 m0, s67
	ds_read_b128 v[202:205], v0
	ds_read_b128 v[206:209], v0 offset:1024
	ds_read_b128 v[210:213], v0 offset:2048
	ds_read_b128 v[214:217], v0 offset:3072
	global_load_lds_dwordx4 v[150:151], off
	v_lshl_add_u64 v[184:185], s[10:11], 0, v[136:137]
	s_add_i32 m0, s67, 0x2000
	s_nop 0
	global_load_lds_dwordx4 v[184:185], off
	s_barrier
	s_waitcnt lgkmcnt(0)
	s_setprio 1
	s_waitcnt lgkmcnt(0)
	v_mfma_f32_16x16x32_bf16 v[62:65], v[202:205], v[164:167], v[62:65]
	v_mfma_f32_16x16x32_bf16 v[58:61], v[210:213], v[164:167], v[58:61]
	v_mfma_f32_16x16x32_bf16 v[54:57], v[202:205], v[172:175], v[54:57]
	v_mfma_f32_16x16x32_bf16 v[50:53], v[210:213], v[172:175], v[50:53]
	v_mfma_f32_16x16x32_bf16 v[46:49], v[202:205], v[180:183], v[46:49]
	v_mfma_f32_16x16x32_bf16 v[42:45], v[210:213], v[180:183], v[42:45]
	v_mfma_f32_16x16x32_bf16 v[38:41], v[202:205], v[194:197], v[38:41]
	v_mfma_f32_16x16x32_bf16 v[34:37], v[210:213], v[194:197], v[34:37]
	v_mfma_f32_16x16x32_bf16 v[62:65], v[206:209], v[168:171], v[62:65]
	v_mfma_f32_16x16x32_bf16 v[58:61], v[214:217], v[168:171], v[58:61]
	v_mfma_f32_16x16x32_bf16 v[54:57], v[206:209], v[176:179], v[54:57]
	v_mfma_f32_16x16x32_bf16 v[50:53], v[214:217], v[176:179], v[50:53]
	v_mfma_f32_16x16x32_bf16 v[46:49], v[206:209], v[190:193], v[46:49]
	v_mfma_f32_16x16x32_bf16 v[42:45], v[214:217], v[190:193], v[42:45]
	v_mfma_f32_16x16x32_bf16 v[38:41], v[206:209], v[198:201], v[38:41]
	v_mfma_f32_16x16x32_bf16 v[34:37], v[214:217], v[198:201], v[34:37]
	s_setprio 0
	s_mov_b32 m0, s85
	v_lshl_add_u64 v[186:187], s[12:13], 0, v[130:131]
	s_barrier
	ds_read_b128 v[164:167], v155 offset:16384
	ds_read_b128 v[168:171], v155 offset:17408
	ds_read_b128 v[172:175], v155 offset:18432
	ds_read_b128 v[176:179], v155 offset:19456
	ds_read_b128 v[180:183], v155 offset:20480
	ds_read_b128 v[190:193], v155 offset:21504
	ds_read_b128 v[194:197], v155 offset:22528
	ds_read_b128 v[198:201], v155 offset:23552
	global_load_lds_dwordx4 v[186:187], off
	v_lshl_add_u64 v[218:219], s[12:13], 0, v[134:135]
	s_mov_b32 m0, s86
	s_nop 0
	global_load_lds_dwordx4 v[218:219], off
	s_barrier
	s_waitcnt lgkmcnt(0)
	s_setprio 1
	s_waitcnt lgkmcnt(0)
	v_mfma_f32_16x16x32_bf16 v[94:97], v[142:145], v[164:167], v[94:97]
	v_mfma_f32_16x16x32_bf16 v[90:93], v[156:159], v[164:167], v[90:93]
	v_mfma_f32_16x16x32_bf16 v[86:89], v[142:145], v[172:175], v[86:89]
	v_mfma_f32_16x16x32_bf16 v[82:85], v[156:159], v[172:175], v[82:85]
	v_mfma_f32_16x16x32_bf16 v[78:81], v[142:145], v[180:183], v[78:81]
	v_mfma_f32_16x16x32_bf16 v[74:77], v[156:159], v[180:183], v[74:77]
	v_mfma_f32_16x16x32_bf16 v[70:73], v[142:145], v[194:197], v[70:73]
	v_mfma_f32_16x16x32_bf16 v[66:69], v[156:159], v[194:197], v[66:69]
	v_mfma_f32_16x16x32_bf16 v[94:97], v[146:149], v[168:171], v[94:97]
	v_mfma_f32_16x16x32_bf16 v[90:93], v[160:163], v[168:171], v[90:93]
	v_mfma_f32_16x16x32_bf16 v[86:89], v[146:149], v[176:179], v[86:89]
	v_mfma_f32_16x16x32_bf16 v[82:85], v[160:163], v[176:179], v[82:85]
	v_mfma_f32_16x16x32_bf16 v[78:81], v[146:149], v[190:193], v[78:81]
	v_mfma_f32_16x16x32_bf16 v[74:77], v[160:163], v[190:193], v[74:77]
	v_mfma_f32_16x16x32_bf16 v[70:73], v[146:149], v[198:201], v[70:73]
	v_mfma_f32_16x16x32_bf16 v[66:69], v[160:163], v[198:201], v[66:69]
	s_setprio 0
	s_barrier
; #define PG8_STAGE(bufoff, gbase, voff) do { _Pragma("unroll") for (int _i = 0; _i < 2; ++_i) \
;     __builtin_amdgcn_global_load_lds((const unsigned*)((const char*)(gbase) + (voff)[_i]), (LAS unsigned*)(lds + (bufoff) + ldsw + _i * 8192), 16, 0, 0); } while (0)
; #define PG8_LDA(dst, b, h) do { _Pragma("unroll") for (int m = 0; m < 4; ++m) _Pragma("unroll") for (int k = 0; k < 2; ++k) dst[m][k] = *(const LAS bf16x8*)(lds + PG8_SA(b, h) + aoff + m * 2048 + k * 1024); } while (0)
; #define PG8_LDB(dst, b, h) do { _Pragma("unroll") for (int n = 0; n < 2; ++n) _Pragma("unroll") for (int k = 0; k < 2; ++k) dst[n][k] = *(const LAS bf16x8*)(lds + PG8_SB(b, h) + boff + n * 2048 + k * 1024); } while (0)
; #define PG8_MMA(ai, bj, At, Bt) do { __builtin_amdgcn_s_setprio(1); _Pragma("unroll") for (int m = 0; m < 4; ++m) _Pragma("unroll") for (int n = 0; n < 2; ++n) _Pragma("unroll") for (int k = 0; k < 2; ++k) \
;     acc[ai][bj][m][n] = __builtin_amdgcn_mfma_f32_16x16x32_bf16(Bt[n][k], At[m][k], acc[ai][bj][m][n], 0, 0, 0); __builtin_amdgcn_s_setprio(0); } while (0)
; #define PG8_WAIT_V(n) asm volatile("s_waitcnt vmcnt(" #n ")" ::: "memory")
; #define PG8_WAIT_L(n) asm volatile("s_waitcnt lgkmcnt(" #n ")" ::: "memory")
; #define PG8_BAR __builtin_amdgcn_s_barrier()
; #define PG8_SCHED __builtin_amdgcn_sched_barrier(0)
; template <class Epi, class Sched>
; DI void gemm_phase(LAS unsigned char* lds, const Gemm g, const Sched& S, const Epi& E, int wid_k) {
;     ...
;       PG8_WAIT_V(6); PG8_BAR; PG8_MMA(1, 1, At, B1); PG8_BAR;
;       PG8_LDB(B0, 1, 0); PG8_SCHED; PG8_LDA(At, 1, 0); PG8_STAGE(PG8_SA(0, 1), a2 + hstepA, voffA);
;       PG8_WAIT_L(8); PG8_BAR; PG8_WAIT_L(0); PG8_MMA(0, 0, At, B0); PG8_BAR; PG8_SCHED;
;       PG8_LDB(B1, 1, 1); PG8_STAGE(PG8_SB(1, 0), b3, voffB);
;       PG8_BAR; PG8_WAIT_L(0); PG8_MMA(0, 1, At, B1); PG8_BAR;
;       PG8_LDA(At, 1, 1); PG8_STAGE(PG8_SA(1, 0), a3, voffA);
;       PG8_BAR; PG8_WAIT_L(0); PG8_MMA(1, 0, At, B0); PG8_BAR; PG8_SCHED;
;       PG8_STAGE(PG8_SB(1, 1), b3 + hstepB, voffB);
	s_add_u32 s68, s10, 0x40000
	s_addc_u32 s69, s11, 0
	s_add_i32 s67, s70, s31
	v_lshl_add_u64 v[142:143], s[68:69], 0, v[132:133]
	s_mov_b32 m0, s67
	s_nop 0
	global_load_lds_dwordx4 v[142:143], off
	v_lshl_add_u64 v[142:143], s[68:69], 0, v[136:137]
	s_add_i32 m0, s67, 0x2000
	s_nop 0
	global_load_lds_dwordx4 v[142:143], off
	s_waitcnt vmcnt(6)
	s_barrier
	s_setprio 1
	v_mfma_f32_16x16x32_bf16 v[30:33], v[202:205], v[164:167], v[30:33]
	v_mfma_f32_16x16x32_bf16 v[26:29], v[210:213], v[164:167], v[26:29]
	v_mfma_f32_16x16x32_bf16 v[22:25], v[202:205], v[172:175], v[22:25]
	v_mfma_f32_16x16x32_bf16 v[18:21], v[210:213], v[172:175], v[18:21]
	v_mfma_f32_16x16x32_bf16 v[14:17], v[202:205], v[180:183], v[14:17]
	v_mfma_f32_16x16x32_bf16 v[10:13], v[210:213], v[180:183], v[10:13]
	v_mfma_f32_16x16x32_bf16 v[6:9], v[202:205], v[194:197], v[6:9]
	v_mfma_f32_16x16x32_bf16 v[2:5], v[210:213], v[194:197], v[2:5]
	v_mfma_f32_16x16x32_bf16 v[30:33], v[206:209], v[168:171], v[30:33]
	v_mfma_f32_16x16x32_bf16 v[26:29], v[214:217], v[168:171], v[26:29]
	v_mfma_f32_16x16x32_bf16 v[22:25], v[206:209], v[176:179], v[22:25]
	v_mfma_f32_16x16x32_bf16 v[18:21], v[214:217], v[176:179], v[18:21]
	v_mfma_f32_16x16x32_bf16 v[14:17], v[206:209], v[190:193], v[14:17]
	v_mfma_f32_16x16x32_bf16 v[10:13], v[214:217], v[190:193], v[10:13]
	v_mfma_f32_16x16x32_bf16 v[6:9], v[206:209], v[198:201], v[6:9]
	v_mfma_f32_16x16x32_bf16 v[2:5], v[214:217], v[198:201], v[2:5]
	s_setprio 0
	s_add_i32 s67, 0, 0x18000
	v_add_u32_e32 v0, s67, v154
	s_barrier
	ds_read_b128 v[142:145], v0
	ds_read_b128 v[146:149], v0 offset:1024
	ds_read_b128 v[156:159], v0 offset:2048
	ds_read_b128 v[160:163], v0 offset:3072
	s_add_u32 s12, s12, 0x40000
	s_addc_u32 s13, s13, 0
	s_mov_b32 m0, s87
	v_lshl_add_u64 v[202:203], s[12:13], 0, v[130:131]
	ds_read_b128 v[164:167], v155 offset:32768
	ds_read_b128 v[168:171], v155 offset:33792
	ds_read_b128 v[172:175], v155 offset:34816
	ds_read_b128 v[176:179], v155 offset:35840
	ds_read_b128 v[180:183], v155 offset:36864
	ds_read_b128 v[190:193], v155 offset:37888
	ds_read_b128 v[194:197], v155 offset:38912
	ds_read_b128 v[198:201], v155 offset:39936
	global_load_lds_dwordx4 v[202:203], off
	v_lshl_add_u64 v[202:203], s[12:13], 0, v[134:135]
	s_mov_b32 m0, s62
	s_nop 0
	global_load_lds_dwordx4 v[202:203], off
	s_waitcnt lgkmcnt(8)
	s_barrier
	s_waitcnt lgkmcnt(0)
	s_setprio 1
	s_waitcnt lgkmcnt(0)
	v_mfma_f32_16x16x32_bf16 v[126:129], v[142:145], v[164:167], v[126:129]
	v_mfma_f32_16x16x32_bf16 v[122:125], v[156:159], v[164:167], v[122:125]
	v_mfma_f32_16x16x32_bf16 v[118:121], v[142:145], v[172:175], v[118:121]
	v_mfma_f32_16x16x32_bf16 v[114:117], v[156:159], v[172:175], v[114:117]
	v_mfma_f32_16x16x32_bf16 v[110:113], v[142:145], v[180:183], v[110:113]
	v_mfma_f32_16x16x32_bf16 v[106:109], v[156:159], v[180:183], v[106:109]
	v_mfma_f32_16x16x32_bf16 v[102:105], v[142:145], v[194:197], v[102:105]
	v_mfma_f32_16x16x32_bf16 v[98:101], v[156:159], v[194:197], v[98:101]
	v_mfma_f32_16x16x32_bf16 v[126:129], v[146:149], v[168:171], v[126:129]
	v_mfma_f32_16x16x32_bf16 v[122:125], v[160:163], v[168:171], v[122:125]
	v_mfma_f32_16x16x32_bf16 v[118:121], v[146:149], v[176:179], v[118:121]
	v_mfma_f32_16x16x32_bf16 v[114:117], v[160:163], v[176:179], v[114:117]
	v_mfma_f32_16x16x32_bf16 v[110:113], v[146:149], v[190:193], v[110:113]
	v_mfma_f32_16x16x32_bf16 v[106:109], v[160:163], v[190:193], v[106:109]
	v_mfma_f32_16x16x32_bf16 v[102:105], v[146:149], v[198:201], v[102:105]
	v_mfma_f32_16x16x32_bf16 v[98:101], v[160:163], v[198:201], v[98:101]
	s_setprio 0
	s_barrier
	s_add_i32 s12, 0, 0x1c000
	s_add_i32 s13, s67, s31
	v_add_u32_e32 v0, s12, v154
	v_lshl_add_u64 v[150:151], v[150:151], 0, s[78:79]
	s_mov_b32 m0, s13
	ds_read_b128 v[202:205], v0
	ds_read_b128 v[206:209], v0 offset:1024
	ds_read_b128 v[210:213], v0 offset:2048
	ds_read_b128 v[214:217], v0 offset:3072
	global_load_lds_dwordx4 v[150:151], off
	v_lshl_add_u64 v[150:151], v[184:185], 0, s[78:79]
	s_add_i32 m0, s13, 0x2000
	s_nop 0
	global_load_lds_dwordx4 v[150:151], off
	s_barrier
	s_waitcnt lgkmcnt(0)
	s_setprio 1
	s_waitcnt lgkmcnt(0)
	v_mfma_f32_16x16x32_bf16 v[62:65], v[202:205], v[164:167], v[62:65]
	v_mfma_f32_16x16x32_bf16 v[58:61], v[210:213], v[164:167], v[58:61]
	v_mfma_f32_16x16x32_bf16 v[54:57], v[202:205], v[172:175], v[54:57]
	v_mfma_f32_16x16x32_bf16 v[50:53], v[210:213], v[172:175], v[50:53]
	v_mfma_f32_16x16x32_bf16 v[46:49], v[202:205], v[180:183], v[46:49]
	v_mfma_f32_16x16x32_bf16 v[42:45], v[210:213], v[180:183], v[42:45]
	v_mfma_f32_16x16x32_bf16 v[38:41], v[202:205], v[194:197], v[38:41]
	v_mfma_f32_16x16x32_bf16 v[34:37], v[210:213], v[194:197], v[34:37]
	v_mfma_f32_16x16x32_bf16 v[62:65], v[206:209], v[168:171], v[62:65]
	v_mfma_f32_16x16x32_bf16 v[58:61], v[214:217], v[168:171], v[58:61]
	v_mfma_f32_16x16x32_bf16 v[54:57], v[206:209], v[176:179], v[54:57]
	v_mfma_f32_16x16x32_bf16 v[50:53], v[214:217], v[176:179], v[50:53]
	v_mfma_f32_16x16x32_bf16 v[46:49], v[206:209], v[190:193], v[46:49]
	v_mfma_f32_16x16x32_bf16 v[42:45], v[214:217], v[190:193], v[42:45]
	v_mfma_f32_16x16x32_bf16 v[38:41], v[206:209], v[198:201], v[38:41]
	v_mfma_f32_16x16x32_bf16 v[34:37], v[214:217], v[198:201], v[34:37]
	s_setprio 0
	s_mov_b32 m0, s63
	v_lshl_add_u64 v[150:151], v[186:187], 0, s[78:79]
	s_barrier
	ds_read_b128 v[164:167], v155 offset:49152
	ds_read_b128 v[168:171], v155 offset:50176
	ds_read_b128 v[172:175], v155 offset:51200
	ds_read_b128 v[176:179], v155 offset:52224
	ds_read_b128 v[180:183], v155 offset:53248
	ds_read_b128 v[190:193], v155 offset:54272
	ds_read_b128 v[194:197], v155 offset:55296
	ds_read_b128 v[198:201], v155 offset:56320
	global_load_lds_dwordx4 v[150:151], off
	v_lshl_add_u64 v[150:151], v[218:219], 0, s[78:79]
	s_mov_b32 m0, s80
	s_nop 0
	global_load_lds_dwordx4 v[150:151], off
	s_barrier
; DI uint4 pack8(f32x4 a, f32x4 b) { uint4 r; r.x = pack2(a[0], a[1]); r.y = pack2(a[2], a[3]); r.z = pack2(b[0], b[1]); r.w = pack2(b[2], b[3]); return r; }
; DI float sigmoidf_(float x) { return 1.f / (1.f + __expf(-x)); }
; #define PG8_STAGE(bufoff, gbase, voff) do { _Pragma("unroll") for (int _i = 0; _i < 2; ++_i) \
;     __builtin_amdgcn_global_load_lds((const unsigned*)((const char*)(gbase) + (voff)[_i]), (LAS unsigned*)(lds + (bufoff) + ldsw + _i * 8192), 16, 0, 0); } while (0)
; #define PG8_MMA(ai, bj, At, Bt) do { __builtin_amdgcn_s_setprio(1); _Pragma("unroll") for (int m = 0; m < 4; ++m) _Pragma("unroll") for (int n = 0; n < 2; ++n) _Pragma("unroll") for (int k = 0; k < 2; ++k) \
;     acc[ai][bj][m][n] = __builtin_amdgcn_mfma_f32_16x16x32_bf16(Bt[n][k], At[m][k], acc[ai][bj][m][n], 0, 0, 0); __builtin_amdgcn_s_setprio(0); } while (0)
; #define PG8_WAIT_V(n) asm volatile("s_waitcnt vmcnt(" #n ")" ::: "memory")
; #define PG8_WAIT_L(n) asm volatile("s_waitcnt lgkmcnt(" #n ")" ::: "memory")
; #define PG8_BAR __builtin_amdgcn_s_barrier()
; #define PG8_SCHED __builtin_amdgcn_sched_barrier(0)
; template <class Epi, class Sched>
; DI void gemm_phase(LAS unsigned char* lds, const Gemm g, const Sched& S, const Epi& E, int wid_k) {
;     ...
;       PG8_BAR; PG8_WAIT_L(0); PG8_MMA(1, 0, At, B0); PG8_BAR; PG8_SCHED;
;       PG8_STAGE(PG8_SB(1, 1), b3 + hstepB, voffB);
;       PG8_WAIT_V(6); PG8_BAR; PG8_MMA(1, 1, At, B1); PG8_BAR;
;     }
;   DI void operator()(const Acc8& acc, const pg8::Unit& u, int wr, int wc, int fr, int fq) const {
;     ...
;           else {
; #pragma unroll
;             for (int e = 0; e < 4; ++e) { v0[e] = sigmoidf_(v0[e]); v1[e] = sigmoidf_(v1[e]); }
;             *(uint4*)(gates + (size_t)row * 3072 + (c8 - 2560)) = pack8(v0, v1);
	s_waitcnt lgkmcnt(0)
	s_setprio 1
	s_waitcnt lgkmcnt(0)
	v_mfma_f32_16x16x32_bf16 v[94:97], v[142:145], v[164:167], v[94:97]
	v_mfma_f32_16x16x32_bf16 v[90:93], v[156:159], v[164:167], v[90:93]
	v_mfma_f32_16x16x32_bf16 v[86:89], v[142:145], v[172:175], v[86:89]
	v_mfma_f32_16x16x32_bf16 v[82:85], v[156:159], v[172:175], v[82:85]
	v_mfma_f32_16x16x32_bf16 v[78:81], v[142:145], v[180:183], v[78:81]
	v_mfma_f32_16x16x32_bf16 v[74:77], v[156:159], v[180:183], v[74:77]
	v_mfma_f32_16x16x32_bf16 v[70:73], v[142:145], v[194:197], v[70:73]
	v_mfma_f32_16x16x32_bf16 v[66:69], v[156:159], v[194:197], v[66:69]
	v_mfma_f32_16x16x32_bf16 v[94:97], v[146:149], v[168:171], v[94:97]
	v_mfma_f32_16x16x32_bf16 v[90:93], v[160:163], v[168:171], v[90:93]
	v_mfma_f32_16x16x32_bf16 v[86:89], v[146:149], v[176:179], v[86:89]
	v_mfma_f32_16x16x32_bf16 v[82:85], v[160:163], v[176:179], v[82:85]
	v_mfma_f32_16x16x32_bf16 v[78:81], v[146:149], v[190:193], v[78:81]
	v_mfma_f32_16x16x32_bf16 v[74:77], v[160:163], v[190:193], v[74:77]
	v_mfma_f32_16x16x32_bf16 v[70:73], v[146:149], v[198:201], v[70:73]
	v_mfma_f32_16x16x32_bf16 v[66:69], v[160:163], v[198:201], v[66:69]
	s_setprio 0
	s_barrier
	s_add_u32 s10, s10, 0x40080
	s_addc_u32 s11, s11, 0
	s_add_i32 s12, s12, s31
	v_lshl_add_u64 v[142:143], s[10:11], 0, v[132:133]
	s_mov_b32 m0, s12
	s_nop 0
	global_load_lds_dwordx4 v[142:143], off
	v_lshl_add_u64 v[142:143], s[10:11], 0, v[136:137]
	s_add_i32 m0, s12, 0x2000
	s_nop 0
	global_load_lds_dwordx4 v[142:143], off
	s_waitcnt vmcnt(6)
	s_barrier
	s_setprio 1
	v_mfma_f32_16x16x32_bf16 v[30:33], v[202:205], v[164:167], v[30:33]
	v_mfma_f32_16x16x32_bf16 v[26:29], v[210:213], v[164:167], v[26:29]
	v_mfma_f32_16x16x32_bf16 v[22:25], v[202:205], v[172:175], v[22:25]
	v_mfma_f32_16x16x32_bf16 v[18:21], v[210:213], v[172:175], v[18:21]
	v_mfma_f32_16x16x32_bf16 v[14:17], v[202:205], v[180:183], v[14:17]
	v_mfma_f32_16x16x32_bf16 v[10:13], v[210:213], v[180:183], v[10:13]
	v_mfma_f32_16x16x32_bf16 v[6:9], v[202:205], v[194:197], v[6:9]
	v_mfma_f32_16x16x32_bf16 v[2:5], v[210:213], v[194:197], v[2:5]
	v_mfma_f32_16x16x32_bf16 v[30:33], v[206:209], v[168:171], v[30:33]
	v_mfma_f32_16x16x32_bf16 v[26:29], v[214:217], v[168:171], v[26:29]
	v_mfma_f32_16x16x32_bf16 v[22:25], v[206:209], v[176:179], v[22:25]
	v_mfma_f32_16x16x32_bf16 v[18:21], v[214:217], v[176:179], v[18:21]
	v_mfma_f32_16x16x32_bf16 v[14:17], v[206:209], v[190:193], v[14:17]
	v_mfma_f32_16x16x32_bf16 v[10:13], v[214:217], v[190:193], v[10:13]
	v_mfma_f32_16x16x32_bf16 v[6:9], v[206:209], v[198:201], v[6:9]
	v_mfma_f32_16x16x32_bf16 v[2:5], v[214:217], v[198:201], v[2:5]
	s_setprio 0
	s_add_i32 s66, s66, 2
	s_add_u32 s8, s8, 0x100
	s_addc_u32 s9, s9, 0
	s_add_u32 s48, s48, 0x100
	s_addc_u32 s49, s49, 0
	s_cmp_gt_u32 s66, 13
	s_barrier
	s_cbranch_scc0 .LBB0_561
	v_mov_b32_e32 v0, v153
	v_mov_b32_e32 v142, v152
	s_mov_b32 s5, s72
	s_mov_b32 s7, s30
	s_lshl_b32 s6, s6, 8
	s_lshl_b32 s39, s5, 5
	s_add_i32 s39, s39, s6
	s_lshl_b32 s4, s4, 8
	s_lshl_b32 s5, s7, 6
	s_add_i32 s5, s5, s4
	s_add_i32 s4, s39, 0x400
	s_cmp_lt_u32 s39, 0x7ffffc00
	s_cselect_b64 s[10:11], -1, 0
	s_cmpk_gt_u32 s4, 0x6ff
	s_cselect_b64 s[90:91], -1, 0
	s_cmpk_gt_u32 s4, 0x87f
	s_cselect_b64 s[66:67], -1, 0
	s_cmpk_gt_u32 s4, 0x97f
	v_lshlrev_b32_e32 v157, 3, v0
	s_cselect_b64 s[48:49], -1, 0
	s_cmpk_gt_u32 s4, 0x9bf
	v_add_u32_e32 v146, s4, v157
	s_cselect_b64 s[70:71], -1, 0
	s_cmpk_gt_u32 s4, 0x9ff
	s_movk_i32 s4, 0x9c0
	v_add_u32_e32 v0, s39, v157
	v_add_u32_e32 v142, s5, v142
	v_cmp_eq_u32_e64 s[8:9], s4, v146
	v_cmp_lt_u32_e64 s[6:7], s76, v0
	v_and_b32_e32 v0, 0xffffff00, v0
	s_movk_i32 s4, 0x100
	s_cselect_b64 s[68:69], -1, 0
	v_ashrrev_i32_e32 v147, 31, v146
	v_bfe_u32 v159, v146, 6, 2
	v_and_b32_e32 v158, 56, v146
	v_cmp_ne_u32_e64 s[4:5], s4, v0
	v_ashrrev_i32_e32 v144, 12, v142
	v_and_b32_e32 v156, 0xfff, v142
	s_mov_b64 s[12:13], -1
	s_and_b64 vcc, exec, s[10:11]
	s_cbranch_vccz .LBB0_594
	s_and_b64 vcc, exec, s[90:91]
	s_cbranch_vccz .LBB0_583
	s_and_b64 vcc, exec, s[66:67]
	s_cbranch_vccz .LBB0_580
	s_and_b64 vcc, exec, s[48:49]
	s_cbranch_vccz .LBB0_577
	s_and_b64 vcc, exec, s[70:71]
	s_cbranch_vccz .LBB0_574
	s_andn2_b64 vcc, exec, s[68:69]
	s_cbranch_vccnz .LBB0_569
	v_mul_f32_e32 v0, 0xbfb8aa3b, v126
	v_exp_f32_e32 v148, v0
	v_mul_f32_e32 v0, 0xbfb8aa3b, v122
	v_exp_f32_e32 v150, v0
	v_mul_f32_e32 v0, 0xbfb8aa3b, v127
	v_exp_f32_e32 v149, v0
	s_nop 0
	v_pk_add_f32 v[148:149], v[148:149], 1.0 op_sel_hi:[1,0]
	s_nop 0
	s_nop 0
	v_rcp_f32_e32 v0, v149
	v_mul_f32_e32 v145, 0xbfb8aa3b, v123
	v_exp_f32_e32 v151, v145
	v_rcp_f32_e32 v143, v148
	v_pk_add_f32 v[148:149], v[150:151], 1.0 op_sel_hi:[1,0]
	s_nop 0
	s_nop 0
	v_rcp_f32_e32 v145, v149
	s_nop 0
	v_rcp_f32_e32 v160, v148
	v_mul_f32_e32 v149, 0xbfb8aa3b, v124
	v_mul_f32_e32 v148, 0xbfb8aa3b, v128
	v_exp_f32_e32 v150, v149
	v_mul_f32_e32 v149, 0xbfb8aa3b, v129
	v_exp_f32_e32 v148, v148
	v_exp_f32_e32 v149, v149
	s_nop 0
	v_pk_add_f32 v[148:149], v[148:149], 1.0 op_sel_hi:[1,0]
	s_nop 0
	s_nop 0
	v_rcp_f32_e32 v161, v149
	s_nop 0
	v_rcp_f32_e32 v162, v148
	v_mul_f32_e32 v148, 0xbfb8aa3b, v125
	v_exp_f32_e32 v151, v148
	s_nop 0
	v_pk_add_f32 v[148:149], v[150:151], 1.0 op_sel_hi:[1,0]
	s_nop 0
	s_nop 0
	v_rcp_f32_e32 v151, v149
	v_readlane_b32 s12, v255, 34
	v_readlane_b32 s13, v255, 35
	v_rcp_f32_e32 v163, v148
	v_cvt_pk_bf16_f32 v149, v162, v161
	v_cvt_pk_bf16_f32 v150, v160, v145
	v_mov_b64_e32 v[160:161], s[12:13]
	s_movk_i32 s12, 0x1800
	v_mad_i64_i32 v[160:161], s[12:13], v142, s12, v[160:161]
	v_lshl_add_u64 v[160:161], v[146:147], 1, v[160:161]
	v_add_co_u32_e32 v160, vcc, 0xfffff000, v160
	v_cvt_pk_bf16_f32 v148, v143, v0
	v_cvt_pk_bf16_f32 v151, v163, v151
	v_addc_co_u32_e32 v161, vcc, -1, v161, vcc
	s_mov_b64 s[12:13], 0
	global_store_dwordx4 v[160:161], v[148:151], off offset:-1024

; DI uint4 pack8(f32x4 a, f32x4 b) { uint4 r; r.x = pack2(a[0], a[1]); r.y = pack2(a[2], a[3]); r.z = pack2(b[0], b[1]); r.w = pack2(b[2], b[3]); return r; }
; DI float sigmoidf_(float x) { return 1.f / (1.f + __expf(-x)); }
;   DI void operator()(const Acc8& acc, const pg8::Unit& u, int wr, int wc, int fr, int fq) const {
;     ...
;           else {
; #pragma unroll
;             for (int e = 0; e < 4; ++e) { v0[e] = sigmoidf_(v0[e]); v1[e] = sigmoidf_(v1[e]); }
;             *(uint4*)(gates + (size_t)row * 3072 + (c8 - 2560)) = pack8(v0, v1);
.LBB0_596:
	v_cndmask_b32_e64 v0, 0, 1, s[10:11]
	v_add_u32_e32 v122, 16, v142
	v_cmp_ne_u32_e64 s[12:13], 1, v0
	v_cndmask_b32_e64 v0, 0, 1, s[90:91]
	v_ashrrev_i32_e32 v124, 12, v122
	v_and_b32_e32 v148, 0xfff, v122
	s_mov_b64 s[94:95], -1
	s_andn2_b64 vcc, exec, s[10:11]
	v_cmp_ne_u32_e64 s[10:11], 1, v0
	s_cbranch_vccnz .LBB0_628
	s_and_b64 vcc, exec, s[10:11]
	s_mov_b64 s[90:91], -1
	s_cbranch_vccnz .LBB0_617
	s_andn2_b64 vcc, exec, s[66:67]
	s_cbranch_vccnz .LBB0_614
	s_andn2_b64 vcc, exec, s[48:49]
	s_cbranch_vccnz .LBB0_611
	s_andn2_b64 vcc, exec, s[70:71]
	s_cbranch_vccnz .LBB0_608
	s_andn2_b64 vcc, exec, s[68:69]
	s_cbranch_vccnz .LBB0_603
	v_mul_f32_e32 v0, 0xbfb8aa3b, v118
	v_exp_f32_e32 v126, v0
	v_mul_f32_e32 v0, 0xbfb8aa3b, v114
	v_exp_f32_e32 v128, v0
	v_mul_f32_e32 v0, 0xbfb8aa3b, v119
	v_exp_f32_e32 v127, v0
	s_movk_i32 s41, 0x1800
	v_pk_add_f32 v[126:127], v[126:127], 1.0 op_sel_hi:[1,0]
	s_nop 0
	s_nop 0
	v_rcp_f32_e32 v0, v127
	v_mul_f32_e32 v125, 0xbfb8aa3b, v115
	v_exp_f32_e32 v129, v125
	v_rcp_f32_e32 v123, v126
	v_pk_add_f32 v[126:127], v[128:129], 1.0 op_sel_hi:[1,0]
	s_nop 0
	s_nop 0
	v_rcp_f32_e32 v125, v127
	s_nop 0
	v_rcp_f32_e32 v145, v126
	v_mul_f32_e32 v127, 0xbfb8aa3b, v116
	v_mul_f32_e32 v126, 0xbfb8aa3b, v120
	v_exp_f32_e32 v128, v127
	v_mul_f32_e32 v127, 0xbfb8aa3b, v121
	v_exp_f32_e32 v126, v126
	v_exp_f32_e32 v127, v127
	s_nop 0
	v_pk_add_f32 v[126:127], v[126:127], 1.0 op_sel_hi:[1,0]
	s_nop 0
	s_nop 0
	v_rcp_f32_e32 v149, v127
	s_nop 0
	v_rcp_f32_e32 v150, v126
	v_mul_f32_e32 v126, 0xbfb8aa3b, v117
	v_exp_f32_e32 v129, v126
	s_nop 0
	v_pk_add_f32 v[126:127], v[128:129], 1.0 op_sel_hi:[1,0]
	s_nop 0
	s_nop 0
	v_rcp_f32_e32 v129, v127
	v_readlane_b32 s90, v255, 34
	v_readlane_b32 s91, v255, 35
	v_rcp_f32_e32 v151, v126
	v_cvt_pk_bf16_f32 v127, v150, v149
	v_cvt_pk_bf16_f32 v129, v151, v129
	v_mov_b64_e32 v[150:151], s[90:91]
	v_mad_i64_i32 v[150:151], s[90:91], v122, s41, v[150:151]
	v_lshl_add_u64 v[150:151], v[146:147], 1, v[150:151]
	v_add_co_u32_e32 v150, vcc, 0xfffff000, v150
	v_cvt_pk_bf16_f32 v126, v123, v0
	v_cvt_pk_bf16_f32 v128, v145, v125
	v_addc_co_u32_e32 v151, vcc, -1, v151, vcc
	s_mov_b64 s[90:91], 0
	global_store_dwordx4 v[150:151], v[126:129], off offset:-1024

; DI uint4 pack8(f32x4 a, f32x4 b) { uint4 r; r.x = pack2(a[0], a[1]); r.y = pack2(a[2], a[3]); r.z = pack2(b[0], b[1]); r.w = pack2(b[2], b[3]); return r; }
; DI float sigmoidf_(float x) { return 1.f / (1.f + __expf(-x)); }
;   DI void operator()(const Acc8& acc, const pg8::Unit& u, int wr, int wc, int fr, int fq) const {
;     ...
;           else {
; #pragma unroll
;             for (int e = 0; e < 4; ++e) { v0[e] = sigmoidf_(v0[e]); v1[e] = sigmoidf_(v1[e]); }
;             *(uint4*)(gates + (size_t)row * 3072 + (c8 - 2560)) = pack8(v0, v1);
.LBB0_630:
	v_add_u32_e32 v114, 32, v142
	v_ashrrev_i32_e32 v116, 12, v114
	v_and_b32_e32 v126, 0xfff, v114
	s_and_b64 vcc, exec, s[12:13]
	s_mov_b64 s[90:91], -1
	s_mov_b32 s94, s14
	s_cbranch_vccnz .LBB0_662
	s_and_b64 vcc, exec, s[10:11]
	s_cbranch_vccnz .LBB0_651
	s_andn2_b64 vcc, exec, s[66:67]
	s_cbranch_vccnz .LBB0_648
	s_andn2_b64 vcc, exec, s[48:49]
	s_cbranch_vccnz .LBB0_645
	s_andn2_b64 vcc, exec, s[70:71]
	s_cbranch_vccnz .LBB0_642
	s_andn2_b64 vcc, exec, s[68:69]
	s_cbranch_vccnz .LBB0_637
	v_mul_f32_e32 v0, 0xbfb8aa3b, v110
	v_exp_f32_e32 v118, v0
	v_mul_f32_e32 v0, 0xbfb8aa3b, v106
	v_exp_f32_e32 v120, v0
	v_mul_f32_e32 v0, 0xbfb8aa3b, v111
	v_exp_f32_e32 v119, v0
	s_movk_i32 s41, 0x1800
	v_pk_add_f32 v[118:119], v[118:119], 1.0 op_sel_hi:[1,0]
	s_nop 0
	s_nop 0
	v_rcp_f32_e32 v0, v119
	v_mul_f32_e32 v117, 0xbfb8aa3b, v107
	v_exp_f32_e32 v121, v117
	v_rcp_f32_e32 v115, v118
	v_pk_add_f32 v[118:119], v[120:121], 1.0 op_sel_hi:[1,0]
	s_nop 0
	s_nop 0
	v_rcp_f32_e32 v117, v119
	s_nop 0
	v_rcp_f32_e32 v125, v118
	v_mul_f32_e32 v119, 0xbfb8aa3b, v108
	v_mul_f32_e32 v118, 0xbfb8aa3b, v112
	v_exp_f32_e32 v120, v119
	v_mul_f32_e32 v119, 0xbfb8aa3b, v113
	v_exp_f32_e32 v118, v118
	v_exp_f32_e32 v119, v119
	s_nop 0
	v_pk_add_f32 v[118:119], v[118:119], 1.0 op_sel_hi:[1,0]
	s_nop 0
	s_nop 0
	v_rcp_f32_e32 v127, v119
	s_nop 0
	v_rcp_f32_e32 v128, v118
	v_mul_f32_e32 v118, 0xbfb8aa3b, v109
	v_exp_f32_e32 v121, v118
	s_nop 0
	v_pk_add_f32 v[118:119], v[120:121], 1.0 op_sel_hi:[1,0]
	s_nop 0
	s_nop 0
	v_rcp_f32_e32 v121, v119
	v_readlane_b32 s90, v255, 34
	v_readlane_b32 s91, v255, 35
	v_rcp_f32_e32 v129, v118
	v_cvt_pk_bf16_f32 v119, v128, v127
	v_cvt_pk_bf16_f32 v121, v129, v121
	v_mov_b64_e32 v[128:129], s[90:91]
	v_mad_i64_i32 v[128:129], s[90:91], v114, s41, v[128:129]
	v_lshl_add_u64 v[128:129], v[146:147], 1, v[128:129]
	v_add_co_u32_e32 v128, vcc, 0xfffff000, v128
	v_cvt_pk_bf16_f32 v118, v115, v0
	v_cvt_pk_bf16_f32 v120, v125, v117
	v_addc_co_u32_e32 v129, vcc, -1, v129, vcc
	s_mov_b64 s[90:91], 0
	global_store_dwordx4 v[128:129], v[118:121], off offset:-1024

; DI uint4 pack8(f32x4 a, f32x4 b) { uint4 r; r.x = pack2(a[0], a[1]); r.y = pack2(a[2], a[3]); r.z = pack2(b[0], b[1]); r.w = pack2(b[2], b[3]); return r; }
; DI float sigmoidf_(float x) { return 1.f / (1.f + __expf(-x)); }
;   DI void operator()(const Acc8& acc, const pg8::Unit& u, int wr, int wc, int fr, int fq) const {
;     ...
;           else {
; #pragma unroll
;             for (int e = 0; e < 4; ++e) { v0[e] = sigmoidf_(v0[e]); v1[e] = sigmoidf_(v1[e]); }
;             *(uint4*)(gates + (size_t)row * 3072 + (c8 - 2560)) = pack8(v0, v1);
.LBB0_664:
	v_add_u32_e32 v106, 48, v142
	v_ashrrev_i32_e32 v108, 12, v106
	v_and_b32_e32 v118, 0xfff, v106
	s_and_b64 vcc, exec, s[12:13]
	s_mov_b64 s[90:91], -1
	s_cbranch_vccnz .LBB0_696
	s_and_b64 vcc, exec, s[10:11]
	s_cbranch_vccnz .LBB0_685
	s_andn2_b64 vcc, exec, s[66:67]
	s_cbranch_vccnz .LBB0_682
	s_andn2_b64 vcc, exec, s[48:49]
	s_cbranch_vccnz .LBB0_679
	s_andn2_b64 vcc, exec, s[70:71]
	s_cbranch_vccnz .LBB0_676
	s_andn2_b64 vcc, exec, s[68:69]
	s_cbranch_vccnz .LBB0_671
	v_mul_f32_e32 v0, 0xbfb8aa3b, v102
	v_exp_f32_e32 v110, v0
	v_mul_f32_e32 v0, 0xbfb8aa3b, v98
	v_exp_f32_e32 v112, v0
	v_mul_f32_e32 v0, 0xbfb8aa3b, v103
	v_exp_f32_e32 v111, v0
	s_movk_i32 s41, 0x1800
	v_pk_add_f32 v[110:111], v[110:111], 1.0 op_sel_hi:[1,0]
	s_nop 0
	s_nop 0
	v_rcp_f32_e32 v0, v111
	v_mul_f32_e32 v109, 0xbfb8aa3b, v99
	v_exp_f32_e32 v113, v109
	v_rcp_f32_e32 v107, v110
	v_pk_add_f32 v[110:111], v[112:113], 1.0 op_sel_hi:[1,0]
	s_nop 0
	s_nop 0
	v_rcp_f32_e32 v109, v111
	s_nop 0
	v_rcp_f32_e32 v117, v110
	v_mul_f32_e32 v111, 0xbfb8aa3b, v100
	v_mul_f32_e32 v110, 0xbfb8aa3b, v104
	v_exp_f32_e32 v112, v111
	v_mul_f32_e32 v111, 0xbfb8aa3b, v105
	v_exp_f32_e32 v110, v110
	v_exp_f32_e32 v111, v111
	s_nop 0
	v_pk_add_f32 v[110:111], v[110:111], 1.0 op_sel_hi:[1,0]
	s_nop 0
	s_nop 0
	v_rcp_f32_e32 v119, v111
	s_nop 0
	v_rcp_f32_e32 v120, v110
	v_mul_f32_e32 v110, 0xbfb8aa3b, v101
	v_exp_f32_e32 v113, v110
	s_nop 0
	v_pk_add_f32 v[110:111], v[112:113], 1.0 op_sel_hi:[1,0]
	s_nop 0
	s_nop 0
	v_rcp_f32_e32 v113, v111
	v_readlane_b32 s90, v255, 34
	v_readlane_b32 s91, v255, 35
	v_rcp_f32_e32 v121, v110
	v_cvt_pk_bf16_f32 v111, v120, v119
	v_cvt_pk_bf16_f32 v113, v121, v113
	v_mov_b64_e32 v[120:121], s[90:91]
	v_mad_i64_i32 v[120:121], s[90:91], v106, s41, v[120:121]
	v_lshl_add_u64 v[120:121], v[146:147], 1, v[120:121]
	v_add_co_u32_e32 v120, vcc, 0xfffff000, v120
	v_cvt_pk_bf16_f32 v110, v107, v0
	v_cvt_pk_bf16_f32 v112, v117, v109
	v_addc_co_u32_e32 v121, vcc, -1, v121, vcc
	s_mov_b64 s[90:91], 0
	global_store_dwordx4 v[120:121], v[110:113], off offset:-1024

; DI uint4 pack8(f32x4 a, f32x4 b) { uint4 r; r.x = pack2(a[0], a[1]); r.y = pack2(a[2], a[3]); r.z = pack2(b[0], b[1]); r.w = pack2(b[2], b[3]); return r; }
; DI float sigmoidf_(float x) { return 1.f / (1.f + __expf(-x)); }
;   DI void operator()(const Acc8& acc, const pg8::Unit& u, int wr, int wc, int fr, int fq) const {
;     ...
;           else {
; #pragma unroll
;             for (int e = 0; e < 4; ++e) { v0[e] = sigmoidf_(v0[e]); v1[e] = sigmoidf_(v1[e]); }
;             *(uint4*)(gates + (size_t)row * 3072 + (c8 - 2560)) = pack8(v0, v1);
.LBB0_698:
	v_add_u32_e32 v98, 0x80, v142
	v_ashrrev_i32_e32 v100, 12, v98
	v_and_b32_e32 v110, 0xfff, v98
	s_and_b64 vcc, exec, s[12:13]
	s_mov_b64 s[90:91], -1
	s_cbranch_vccnz .LBB0_730
	s_and_b64 vcc, exec, s[10:11]
	s_cbranch_vccnz .LBB0_719
	s_andn2_b64 vcc, exec, s[66:67]
	s_cbranch_vccnz .LBB0_716
	s_andn2_b64 vcc, exec, s[48:49]
	s_cbranch_vccnz .LBB0_713
	s_andn2_b64 vcc, exec, s[70:71]
	s_cbranch_vccnz .LBB0_710
	s_andn2_b64 vcc, exec, s[68:69]
	s_cbranch_vccnz .LBB0_705
	v_mul_f32_e32 v0, 0xbfb8aa3b, v94
	v_exp_f32_e32 v102, v0
	v_mul_f32_e32 v0, 0xbfb8aa3b, v90
	v_exp_f32_e32 v104, v0
	v_mul_f32_e32 v0, 0xbfb8aa3b, v95
	v_exp_f32_e32 v103, v0
	s_movk_i32 s41, 0x1800
	v_pk_add_f32 v[102:103], v[102:103], 1.0 op_sel_hi:[1,0]
	s_nop 0
	s_nop 0
	v_rcp_f32_e32 v0, v103
	v_mul_f32_e32 v101, 0xbfb8aa3b, v91
	v_exp_f32_e32 v105, v101
	v_rcp_f32_e32 v99, v102
	v_pk_add_f32 v[102:103], v[104:105], 1.0 op_sel_hi:[1,0]
	s_nop 0
	s_nop 0
	v_rcp_f32_e32 v101, v103
	s_nop 0
	v_rcp_f32_e32 v109, v102
	v_mul_f32_e32 v103, 0xbfb8aa3b, v92
	v_mul_f32_e32 v102, 0xbfb8aa3b, v96
	v_exp_f32_e32 v104, v103
	v_mul_f32_e32 v103, 0xbfb8aa3b, v97
	v_exp_f32_e32 v102, v102
	v_exp_f32_e32 v103, v103
	s_nop 0
	v_pk_add_f32 v[102:103], v[102:103], 1.0 op_sel_hi:[1,0]
	s_nop 0
	s_nop 0
	v_rcp_f32_e32 v111, v103
	s_nop 0
	v_rcp_f32_e32 v112, v102
	v_mul_f32_e32 v102, 0xbfb8aa3b, v93
	v_exp_f32_e32 v105, v102
	s_nop 0
	v_pk_add_f32 v[102:103], v[104:105], 1.0 op_sel_hi:[1,0]
	s_nop 0
	s_nop 0
	v_rcp_f32_e32 v105, v103
	v_readlane_b32 s90, v255, 34
	v_readlane_b32 s91, v255, 35
	v_rcp_f32_e32 v113, v102
	v_cvt_pk_bf16_f32 v103, v112, v111
	v_cvt_pk_bf16_f32 v105, v113, v105
	v_mov_b64_e32 v[112:113], s[90:91]
	v_mad_i64_i32 v[112:113], s[90:91], v98, s41, v[112:113]
	v_lshl_add_u64 v[112:113], v[146:147], 1, v[112:113]
	v_add_co_u32_e32 v112, vcc, 0xfffff000, v112
	v_cvt_pk_bf16_f32 v102, v99, v0
	v_cvt_pk_bf16_f32 v104, v109, v101
	v_addc_co_u32_e32 v113, vcc, -1, v113, vcc
	s_mov_b64 s[90:91], 0
	global_store_dwordx4 v[112:113], v[102:105], off offset:-1024

; DI uint4 pack8(f32x4 a, f32x4 b) { uint4 r; r.x = pack2(a[0], a[1]); r.y = pack2(a[2], a[3]); r.z = pack2(b[0], b[1]); r.w = pack2(b[2], b[3]); return r; }
; DI float sigmoidf_(float x) { return 1.f / (1.f + __expf(-x)); }
;   DI void operator()(const Acc8& acc, const pg8::Unit& u, int wr, int wc, int fr, int fq) const {
;     ...
;           else {
; #pragma unroll
;             for (int e = 0; e < 4; ++e) { v0[e] = sigmoidf_(v0[e]); v1[e] = sigmoidf_(v1[e]); }
;             *(uint4*)(gates + (size_t)row * 3072 + (c8 - 2560)) = pack8(v0, v1);
.LBB0_732:
	v_add_u32_e32 v90, 0x90, v142
	v_ashrrev_i32_e32 v92, 12, v90
	v_and_b32_e32 v102, 0xfff, v90
	s_and_b64 vcc, exec, s[12:13]
	s_mov_b64 s[90:91], -1
	s_cbranch_vccnz .LBB0_764
	s_and_b64 vcc, exec, s[10:11]
	s_cbranch_vccnz .LBB0_753
	s_andn2_b64 vcc, exec, s[66:67]
	s_cbranch_vccnz .LBB0_750
	s_andn2_b64 vcc, exec, s[48:49]
	s_cbranch_vccnz .LBB0_747
	s_andn2_b64 vcc, exec, s[70:71]
	s_cbranch_vccnz .LBB0_744
	s_andn2_b64 vcc, exec, s[68:69]
	s_cbranch_vccnz .LBB0_739
	v_mul_f32_e32 v0, 0xbfb8aa3b, v86
	v_exp_f32_e32 v94, v0
	v_mul_f32_e32 v0, 0xbfb8aa3b, v82
	v_exp_f32_e32 v96, v0
	v_mul_f32_e32 v0, 0xbfb8aa3b, v87
	v_exp_f32_e32 v95, v0
	s_movk_i32 s41, 0x1800
	v_pk_add_f32 v[94:95], v[94:95], 1.0 op_sel_hi:[1,0]
	s_nop 0
	s_nop 0
	v_rcp_f32_e32 v0, v95
	v_mul_f32_e32 v93, 0xbfb8aa3b, v83
	v_exp_f32_e32 v97, v93
	v_rcp_f32_e32 v91, v94
	v_pk_add_f32 v[94:95], v[96:97], 1.0 op_sel_hi:[1,0]
	s_nop 0
	s_nop 0
	v_rcp_f32_e32 v93, v95
	s_nop 0
	v_rcp_f32_e32 v101, v94
	v_mul_f32_e32 v95, 0xbfb8aa3b, v84
	v_mul_f32_e32 v94, 0xbfb8aa3b, v88
	v_exp_f32_e32 v96, v95
	v_mul_f32_e32 v95, 0xbfb8aa3b, v89
	v_exp_f32_e32 v94, v94
	v_exp_f32_e32 v95, v95
	s_nop 0
	v_pk_add_f32 v[94:95], v[94:95], 1.0 op_sel_hi:[1,0]
	s_nop 0
	s_nop 0
	v_rcp_f32_e32 v103, v95
	s_nop 0
	v_rcp_f32_e32 v104, v94
	v_mul_f32_e32 v94, 0xbfb8aa3b, v85
	v_exp_f32_e32 v97, v94
	s_nop 0
	v_pk_add_f32 v[94:95], v[96:97], 1.0 op_sel_hi:[1,0]
	s_nop 0
	s_nop 0
	v_rcp_f32_e32 v97, v95
	v_readlane_b32 s90, v255, 34
	v_readlane_b32 s91, v255, 35
	v_rcp_f32_e32 v105, v94
	v_cvt_pk_bf16_f32 v95, v104, v103
	v_cvt_pk_bf16_f32 v97, v105, v97
	v_mov_b64_e32 v[104:105], s[90:91]
	v_mad_i64_i32 v[104:105], s[90:91], v90, s41, v[104:105]
	v_lshl_add_u64 v[104:105], v[146:147], 1, v[104:105]
	v_add_co_u32_e32 v104, vcc, 0xfffff000, v104
	v_cvt_pk_bf16_f32 v94, v91, v0
	v_cvt_pk_bf16_f32 v96, v101, v93
	v_addc_co_u32_e32 v105, vcc, -1, v105, vcc
	s_mov_b64 s[90:91], 0
	global_store_dwordx4 v[104:105], v[94:97], off offset:-1024

; DI uint4 pack8(f32x4 a, f32x4 b) { uint4 r; r.x = pack2(a[0], a[1]); r.y = pack2(a[2], a[3]); r.z = pack2(b[0], b[1]); r.w = pack2(b[2], b[3]); return r; }
; DI float sigmoidf_(float x) { return 1.f / (1.f + __expf(-x)); }
;   DI void operator()(const Acc8& acc, const pg8::Unit& u, int wr, int wc, int fr, int fq) const {
;     ...
;           else {
; #pragma unroll
;             for (int e = 0; e < 4; ++e) { v0[e] = sigmoidf_(v0[e]); v1[e] = sigmoidf_(v1[e]); }
;             *(uint4*)(gates + (size_t)row * 3072 + (c8 - 2560)) = pack8(v0, v1);
.LBB0_766:
	v_add_u32_e32 v82, 0xa0, v142
	v_ashrrev_i32_e32 v84, 12, v82
	v_and_b32_e32 v94, 0xfff, v82
	s_and_b64 vcc, exec, s[12:13]
	s_mov_b64 s[90:91], -1
	s_cbranch_vccnz .LBB0_798
	s_and_b64 vcc, exec, s[10:11]
	s_cbranch_vccnz .LBB0_787
	s_andn2_b64 vcc, exec, s[66:67]
	s_cbranch_vccnz .LBB0_784
	s_andn2_b64 vcc, exec, s[48:49]
	s_cbranch_vccnz .LBB0_781
	s_andn2_b64 vcc, exec, s[70:71]
	s_cbranch_vccnz .LBB0_778
	s_andn2_b64 vcc, exec, s[68:69]
	s_cbranch_vccnz .LBB0_773
	v_mul_f32_e32 v0, 0xbfb8aa3b, v78
	v_exp_f32_e32 v86, v0
	v_mul_f32_e32 v0, 0xbfb8aa3b, v74
	v_exp_f32_e32 v88, v0
	v_mul_f32_e32 v0, 0xbfb8aa3b, v79
	v_exp_f32_e32 v87, v0
	s_movk_i32 s41, 0x1800
	v_pk_add_f32 v[86:87], v[86:87], 1.0 op_sel_hi:[1,0]
	s_nop 0
	s_nop 0
	v_rcp_f32_e32 v0, v87
	v_mul_f32_e32 v85, 0xbfb8aa3b, v75
	v_exp_f32_e32 v89, v85
	v_rcp_f32_e32 v83, v86
	v_pk_add_f32 v[86:87], v[88:89], 1.0 op_sel_hi:[1,0]
	s_nop 0
	s_nop 0
	v_rcp_f32_e32 v85, v87
	s_nop 0
	v_rcp_f32_e32 v93, v86
	v_mul_f32_e32 v87, 0xbfb8aa3b, v76
	v_mul_f32_e32 v86, 0xbfb8aa3b, v80
	v_exp_f32_e32 v88, v87
	v_mul_f32_e32 v87, 0xbfb8aa3b, v81
	v_exp_f32_e32 v86, v86
	v_exp_f32_e32 v87, v87
	s_nop 0
	v_pk_add_f32 v[86:87], v[86:87], 1.0 op_sel_hi:[1,0]
	s_nop 0
	s_nop 0
	v_rcp_f32_e32 v95, v87
	s_nop 0
	v_rcp_f32_e32 v96, v86
	v_mul_f32_e32 v86, 0xbfb8aa3b, v77
	v_exp_f32_e32 v89, v86
	s_nop 0
	v_pk_add_f32 v[86:87], v[88:89], 1.0 op_sel_hi:[1,0]
	s_nop 0
	s_nop 0
	v_rcp_f32_e32 v89, v87
	v_readlane_b32 s90, v255, 34
	v_readlane_b32 s91, v255, 35
	v_rcp_f32_e32 v97, v86
	v_cvt_pk_bf16_f32 v87, v96, v95
	v_cvt_pk_bf16_f32 v89, v97, v89
	v_mov_b64_e32 v[96:97], s[90:91]
	v_mad_i64_i32 v[96:97], s[90:91], v82, s41, v[96:97]
	v_lshl_add_u64 v[96:97], v[146:147], 1, v[96:97]
	v_add_co_u32_e32 v96, vcc, 0xfffff000, v96
	v_cvt_pk_bf16_f32 v86, v83, v0
	v_cvt_pk_bf16_f32 v88, v93, v85
	v_addc_co_u32_e32 v97, vcc, -1, v97, vcc
	s_mov_b64 s[90:91], 0
	global_store_dwordx4 v[96:97], v[86:89], off offset:-1024

; DI uint4 pack8(f32x4 a, f32x4 b) { uint4 r; r.x = pack2(a[0], a[1]); r.y = pack2(a[2], a[3]); r.z = pack2(b[0], b[1]); r.w = pack2(b[2], b[3]); return r; }
; DI float sigmoidf_(float x) { return 1.f / (1.f + __expf(-x)); }
;   DI void operator()(const Acc8& acc, const pg8::Unit& u, int wr, int wc, int fr, int fq) const {
;     ...
;           else {
; #pragma unroll
;             for (int e = 0; e < 4; ++e) { v0[e] = sigmoidf_(v0[e]); v1[e] = sigmoidf_(v1[e]); }
;             *(uint4*)(gates + (size_t)row * 3072 + (c8 - 2560)) = pack8(v0, v1);
.LBB0_800:
	v_add_u32_e32 v74, 0xb0, v142
	v_ashrrev_i32_e32 v76, 12, v74
	v_and_b32_e32 v86, 0xfff, v74
	s_and_b64 vcc, exec, s[12:13]
	s_mov_b64 s[12:13], -1
	s_cbranch_vccnz .LBB0_832
	s_and_b64 vcc, exec, s[10:11]
	s_mov_b64 s[10:11], -1
	s_cbranch_vccnz .LBB0_821
	s_andn2_b64 vcc, exec, s[66:67]
	s_cbranch_vccnz .LBB0_818
	s_andn2_b64 vcc, exec, s[48:49]
	s_cbranch_vccnz .LBB0_815
	s_andn2_b64 vcc, exec, s[70:71]
	s_cbranch_vccnz .LBB0_812
	s_andn2_b64 vcc, exec, s[68:69]
	s_cbranch_vccnz .LBB0_807
	v_mul_f32_e32 v0, 0xbfb8aa3b, v70
	v_exp_f32_e32 v78, v0
	v_mul_f32_e32 v0, 0xbfb8aa3b, v66
	v_exp_f32_e32 v80, v0
	v_mul_f32_e32 v0, 0xbfb8aa3b, v71
	v_exp_f32_e32 v79, v0
	s_nop 0
	v_pk_add_f32 v[78:79], v[78:79], 1.0 op_sel_hi:[1,0]
	s_nop 0
	s_nop 0
	v_rcp_f32_e32 v0, v79
	v_mul_f32_e32 v77, 0xbfb8aa3b, v67
	v_exp_f32_e32 v81, v77
	v_rcp_f32_e32 v75, v78
	v_pk_add_f32 v[78:79], v[80:81], 1.0 op_sel_hi:[1,0]
	s_nop 0
	s_nop 0
	v_rcp_f32_e32 v77, v79
	s_nop 0
	v_rcp_f32_e32 v85, v78
	v_mul_f32_e32 v79, 0xbfb8aa3b, v68
	v_mul_f32_e32 v78, 0xbfb8aa3b, v72
	v_exp_f32_e32 v80, v79
	v_mul_f32_e32 v79, 0xbfb8aa3b, v73
	v_exp_f32_e32 v78, v78
	v_exp_f32_e32 v79, v79
	s_nop 0
	v_pk_add_f32 v[78:79], v[78:79], 1.0 op_sel_hi:[1,0]
	s_nop 0
	s_nop 0
	v_rcp_f32_e32 v87, v79
	s_nop 0
	v_rcp_f32_e32 v88, v78
	v_mul_f32_e32 v78, 0xbfb8aa3b, v69
	v_exp_f32_e32 v81, v78
	s_nop 0
	v_pk_add_f32 v[78:79], v[80:81], 1.0 op_sel_hi:[1,0]
	s_nop 0
	s_nop 0
	v_rcp_f32_e32 v81, v79
	v_readlane_b32 s10, v255, 34
	v_readlane_b32 s11, v255, 35
	v_rcp_f32_e32 v89, v78
	v_cvt_pk_bf16_f32 v79, v88, v87
	v_cvt_pk_bf16_f32 v81, v89, v81
	v_mov_b64_e32 v[88:89], s[10:11]
	s_movk_i32 s10, 0x1800
	v_mad_i64_i32 v[88:89], s[10:11], v74, s10, v[88:89]
	v_lshl_add_u64 v[88:89], v[146:147], 1, v[88:89]
	v_add_co_u32_e32 v88, vcc, 0xfffff000, v88
	v_cvt_pk_bf16_f32 v78, v75, v0
	v_cvt_pk_bf16_f32 v80, v85, v77
	v_addc_co_u32_e32 v89, vcc, -1, v89, vcc
	s_mov_b64 s[10:11], 0
	global_store_dwordx4 v[88:89], v[78:81], off offset:-1024

;   DI void operator()(const Acc8& acc, const pg8::Unit& u, int wr, int wc, int fr, int fq) const {
;     ...
;     for (int bj = 0; bj < 2; ++bj) {
;       const int c32 = coff + u.pn * 256 + bj * 128 + wc * 32;
;       const int c8 = c32 + 8 * fq;
; #pragma unroll
;       for (int ai = 0; ai < 2; ++ai)
; #pragma unroll
;         for (int m = 0; m < 4; ++m) {
;           const int row = EPI_ROWS(ai, m); const int b = row >> 12, s = row & 4095;
;           f32x4 v0 = acc[ai][bj][m][0], v1 = acc[ai][bj][m][1];
;           if (c32 < 1024) { *(uint4*)(zraw + (size_t)row * 1024 + c8) = pack8(v0, v1); }
;           else if (c32 < 1792) {
;             const int c = c8 - 1024, part = c >> 8, hc = c & 255, h = hc >> 6, d = hc & 63; const size_t bh = (size_t)b * 4 + h;
;             if (part == 0) { v0 *= 0.18033688f; v1 *= 0.18033688f; *(uint4*)(fq_ + (bh * SEQ + s) * 64 + d) = pack8(v0, v1); }
;             else if (part == 1) { *(uint4*)(fk_ + (bh * SEQ + s) * 64 + d) = pack8(v0, v1); }
;             else {
; #pragma unroll
;               for (int e = 0; e < 4; ++e) { fvT[(bh * 64 + d + e) * SEQ + s] = f2bf(v0[e]); fvT[(bh * 64 + d + 4 + e) * SEQ + s] = f2bf(v1[e]); }
;             }
;           }
;           else if (c32 < 2176) { *(uint4*)(zq + (size_t)row * 384 + (c8 - 1792)) = pack8(v0, v1); }
;           else if (c32 < 2432) { *(uint4*)(zkv + (size_t)row * 256 + (c8 - 2176)) = pack8(v0, v1); }
;           else if (c32 < 2496) { *(uint4*)(zpe + (size_t)row * 64 + (c8 - 2432)) = pack8(v0, v1); }
;           else if (c32 < 2560) {
;             if (c8 == 2496) {
;               float4 lf;
;               { const float x = v0[0] + b_forget[0]; lf.x = fminf(x, 0.f) - log1pf(__expf(-fabsf(x))); }
;               { const float x = v0[1] + b_forget[1]; lf.y = fminf(x, 0.f) - log1pf(__expf(-fabsf(x))); }
;               { const float x = v0[2] + b_forget[2]; lf.z = fminf(x, 0.f) - log1pf(__expf(-fabsf(x))); }
;               { const float x = v0[3] + b_forget[3]; lf.w = fminf(x, 0.f) - log1pf(__expf(-fabsf(x))); }
;               *(float4*)(flog + (size_t)row * 4) = lf;
;             }
;           }
;           else {
; #pragma unroll
;             for (int e = 0; e < 4; ++e) { v0[e] = sigmoidf_(v0[e]); v1[e] = sigmoidf_(v1[e]); }
;             *(uint4*)(gates + (size_t)row * 3072 + (c8 - 2560)) = pack8(v0, v1);
.LBB0_834:
	s_addk_i32 s39, 0x480
	s_cmpk_gt_i32 s39, 0x3ff
	s_cselect_b64 s[90:91], -1, 0
	s_cmpk_gt_u32 s39, 0x6ff
	v_add_u32_e32 v66, s39, v157
	s_cselect_b64 s[10:11], -1, 0
	s_cmpk_gt_u32 s39, 0x87f
	s_cselect_b64 s[66:67], -1, 0
	s_cmpk_gt_u32 s39, 0x97f
	s_movk_i32 s4, 0x9c0
	v_add_u32_e32 v0, 0xfffffc00, v66
	s_cselect_b64 s[48:49], -1, 0
	s_cmpk_gt_u32 s39, 0x9bf
	v_cmp_eq_u32_e64 s[8:9], s4, v66
	v_cmp_lt_u32_e64 s[6:7], s76, v0
	v_and_b32_e32 v0, 0xffffff00, v0
	s_movk_i32 s4, 0x100
	s_cselect_b64 s[70:71], -1, 0
	s_cmpk_gt_u32 s39, 0x9ff
	v_cmp_ne_u32_e64 s[4:5], s4, v0
	v_cndmask_b32_e64 v0, 0, 1, s[10:11]
	s_cselect_b64 s[68:69], -1, 0
	s_cmpk_lt_i32 s39, 0x400
	v_ashrrev_i32_e32 v67, 31, v66
	v_bfe_u32 v73, v66, 6, 2
	v_and_b32_e32 v72, 56, v66
	s_mov_b64 s[12:13], -1
	v_cmp_ne_u32_e64 s[10:11], 1, v0
	s_cbranch_scc1 .LBB0_866
	s_and_b64 vcc, exec, s[10:11]
	s_cbranch_vccnz .LBB0_855
	s_andn2_b64 vcc, exec, s[66:67]
	s_cbranch_vccnz .LBB0_852
	s_andn2_b64 vcc, exec, s[48:49]
	s_cbranch_vccnz .LBB0_849
	s_andn2_b64 vcc, exec, s[70:71]
	s_cbranch_vccnz .LBB0_846
	s_andn2_b64 vcc, exec, s[68:69]
	s_cbranch_vccnz .LBB0_841
	v_mul_f32_e32 v0, 0xbfb8aa3b, v62
	v_exp_f32_e32 v68, v0
	v_mul_f32_e32 v0, 0xbfb8aa3b, v58
	v_exp_f32_e32 v70, v0
	v_mul_f32_e32 v0, 0xbfb8aa3b, v63
	v_exp_f32_e32 v69, v0
	s_nop 0
	v_pk_add_f32 v[68:69], v[68:69], 1.0 op_sel_hi:[1,0]
	s_nop 0
	s_nop 0
	v_rcp_f32_e32 v0, v69
	s_nop 0
	v_rcp_f32_e32 v77, v68
	v_mul_f32_e32 v68, 0xbfb8aa3b, v59
	v_exp_f32_e32 v71, v68
	s_nop 0
	v_pk_add_f32 v[68:69], v[70:71], 1.0 op_sel_hi:[1,0]
	s_nop 0
	s_nop 0
	v_rcp_f32_e32 v78, v69
	s_nop 0
	v_rcp_f32_e32 v79, v68
	v_mul_f32_e32 v69, 0xbfb8aa3b, v60
	v_mul_f32_e32 v68, 0xbfb8aa3b, v64
	v_exp_f32_e32 v70, v69
	v_mul_f32_e32 v69, 0xbfb8aa3b, v65
	v_exp_f32_e32 v68, v68
	v_exp_f32_e32 v69, v69
	s_nop 0
	v_pk_add_f32 v[68:69], v[68:69], 1.0 op_sel_hi:[1,0]
	s_nop 0
	s_nop 0
	v_rcp_f32_e32 v80, v69
	s_nop 0
	v_rcp_f32_e32 v81, v68
	v_mul_f32_e32 v68, 0xbfb8aa3b, v61
	v_exp_f32_e32 v71, v68
	s_nop 0
	v_pk_add_f32 v[68:69], v[70:71], 1.0 op_sel_hi:[1,0]
	s_nop 0
	s_nop 0
	v_rcp_f32_e32 v71, v69
	v_readlane_b32 s12, v255, 34
	v_readlane_b32 s13, v255, 35
	v_cvt_pk_bf16_f32 v70, v79, v78
	s_nop 0
	v_mov_b64_e32 v[78:79], s[12:13]
	s_movk_i32 s12, 0x1800
	v_mad_i64_i32 v[78:79], s[12:13], v142, s12, v[78:79]
	v_lshl_add_u64 v[78:79], v[66:67], 1, v[78:79]
	v_rcp_f32_e32 v85, v68
	v_add_co_u32_e32 v78, vcc, 0xfffff000, v78
	v_cvt_pk_bf16_f32 v68, v77, v0
	v_cvt_pk_bf16_f32 v69, v81, v80
	v_cvt_pk_bf16_f32 v71, v85, v71
	v_addc_co_u32_e32 v79, vcc, -1, v79, vcc
	s_mov_b64 s[12:13], 0
	global_store_dwordx4 v[78:79], v[68:71], off offset:-1024

; DI uint4 pack8(f32x4 a, f32x4 b) { uint4 r; r.x = pack2(a[0], a[1]); r.y = pack2(a[2], a[3]); r.z = pack2(b[0], b[1]); r.w = pack2(b[2], b[3]); return r; }
; DI float sigmoidf_(float x) { return 1.f / (1.f + __expf(-x)); }
;   DI void operator()(const Acc8& acc, const pg8::Unit& u, int wr, int wc, int fr, int fq) const {
;     ...
;           else {
; #pragma unroll
;             for (int e = 0; e < 4; ++e) { v0[e] = sigmoidf_(v0[e]); v1[e] = sigmoidf_(v1[e]); }
;             *(uint4*)(gates + (size_t)row * 3072 + (c8 - 2560)) = pack8(v0, v1);
.LBB0_882:
	s_and_b64 vcc, exec, s[10:11]
	s_cbranch_vccnz .LBB0_902
	s_andn2_b64 vcc, exec, s[66:67]
	s_cbranch_vccnz .LBB0_899
	s_andn2_b64 vcc, exec, s[48:49]
	s_cbranch_vccnz .LBB0_896
	s_andn2_b64 vcc, exec, s[70:71]
	s_cbranch_vccnz .LBB0_893
	s_andn2_b64 vcc, exec, s[68:69]
	s_cbranch_vccnz .LBB0_888
	v_mul_f32_e32 v0, 0xbfb8aa3b, v54
	v_exp_f32_e32 v58, v0
	v_mul_f32_e32 v0, 0xbfb8aa3b, v50
	v_exp_f32_e32 v60, v0
	v_mul_f32_e32 v0, 0xbfb8aa3b, v55
	v_exp_f32_e32 v59, v0
	s_movk_i32 s39, 0x1800
	v_pk_add_f32 v[58:59], v[58:59], 1.0 op_sel_hi:[1,0]
	s_nop 0
	s_nop 0
	v_rcp_f32_e32 v0, v59
	s_nop 0
	v_rcp_f32_e32 v62, v58
	v_mul_f32_e32 v58, 0xbfb8aa3b, v51
	v_exp_f32_e32 v61, v58
	s_nop 0
	v_pk_add_f32 v[58:59], v[60:61], 1.0 op_sel_hi:[1,0]
	s_nop 0
	s_nop 0
	v_rcp_f32_e32 v63, v59
	s_nop 0
	v_rcp_f32_e32 v64, v58
	v_mul_f32_e32 v59, 0xbfb8aa3b, v52
	v_mul_f32_e32 v58, 0xbfb8aa3b, v56
	v_exp_f32_e32 v60, v59
	v_mul_f32_e32 v59, 0xbfb8aa3b, v57
	v_exp_f32_e32 v58, v58
	v_exp_f32_e32 v59, v59
	s_nop 0
	v_pk_add_f32 v[58:59], v[58:59], 1.0 op_sel_hi:[1,0]
	s_nop 0
	s_nop 0
	v_rcp_f32_e32 v65, v59
	s_nop 0
	v_rcp_f32_e32 v68, v58
	v_mul_f32_e32 v58, 0xbfb8aa3b, v53
	v_exp_f32_e32 v61, v58
	s_nop 0
	v_pk_add_f32 v[58:59], v[60:61], 1.0 op_sel_hi:[1,0]
	s_nop 0
	s_nop 0
	v_rcp_f32_e32 v61, v59
	v_readlane_b32 s90, v255, 34
	v_readlane_b32 s91, v255, 35
	v_rcp_f32_e32 v69, v58
	v_cvt_pk_bf16_f32 v58, v62, v0
	v_cvt_pk_bf16_f32 v60, v64, v63
	v_mov_b64_e32 v[62:63], s[90:91]
	v_mad_i64_i32 v[62:63], s[90:91], v122, s39, v[62:63]
	v_lshl_add_u64 v[62:63], v[66:67], 1, v[62:63]
	v_add_co_u32_e32 v62, vcc, 0xfffff000, v62
	v_cvt_pk_bf16_f32 v59, v68, v65
	v_cvt_pk_bf16_f32 v61, v69, v61
	v_addc_co_u32_e32 v63, vcc, -1, v63, vcc
	s_mov_b64 s[90:91], 0
	global_store_dwordx4 v[62:63], v[58:61], off offset:-1024

; DI uint4 pack8(f32x4 a, f32x4 b) { uint4 r; r.x = pack2(a[0], a[1]); r.y = pack2(a[2], a[3]); r.z = pack2(b[0], b[1]); r.w = pack2(b[2], b[3]); return r; }
; DI float sigmoidf_(float x) { return 1.f / (1.f + __expf(-x)); }
;   DI void operator()(const Acc8& acc, const pg8::Unit& u, int wr, int wc, int fr, int fq) const {
;     ...
;           else {
; #pragma unroll
;             for (int e = 0; e < 4; ++e) { v0[e] = sigmoidf_(v0[e]); v1[e] = sigmoidf_(v1[e]); }
;             *(uint4*)(gates + (size_t)row * 3072 + (c8 - 2560)) = pack8(v0, v1);
.LBB0_914:
	s_and_b64 vcc, exec, s[10:11]
	s_cbranch_vccnz .LBB0_934
	s_andn2_b64 vcc, exec, s[66:67]
	s_cbranch_vccnz .LBB0_931
	s_andn2_b64 vcc, exec, s[48:49]
	s_cbranch_vccnz .LBB0_928
	s_andn2_b64 vcc, exec, s[70:71]
	s_cbranch_vccnz .LBB0_925
	s_andn2_b64 vcc, exec, s[68:69]
	s_cbranch_vccnz .LBB0_920
	v_mul_f32_e32 v0, 0xbfb8aa3b, v46
	v_exp_f32_e32 v50, v0
	v_mul_f32_e32 v0, 0xbfb8aa3b, v42
	v_exp_f32_e32 v52, v0
	v_mul_f32_e32 v0, 0xbfb8aa3b, v47
	v_exp_f32_e32 v51, v0
	s_movk_i32 s39, 0x1800
	v_pk_add_f32 v[50:51], v[50:51], 1.0 op_sel_hi:[1,0]
	s_nop 0
	s_nop 0
	v_rcp_f32_e32 v0, v51
	s_nop 0
	v_rcp_f32_e32 v54, v50
	v_mul_f32_e32 v50, 0xbfb8aa3b, v43
	v_exp_f32_e32 v53, v50
	s_nop 0
	v_pk_add_f32 v[50:51], v[52:53], 1.0 op_sel_hi:[1,0]
	s_nop 0
	s_nop 0
	v_rcp_f32_e32 v55, v51
	s_nop 0
	v_rcp_f32_e32 v56, v50
	v_mul_f32_e32 v51, 0xbfb8aa3b, v44
	v_mul_f32_e32 v50, 0xbfb8aa3b, v48
	v_exp_f32_e32 v52, v51
	v_mul_f32_e32 v51, 0xbfb8aa3b, v49
	v_exp_f32_e32 v50, v50
	v_exp_f32_e32 v51, v51
	s_nop 0
	v_pk_add_f32 v[50:51], v[50:51], 1.0 op_sel_hi:[1,0]
	s_nop 0
	s_nop 0
	v_rcp_f32_e32 v57, v51
	s_nop 0
	v_rcp_f32_e32 v58, v50
	v_mul_f32_e32 v50, 0xbfb8aa3b, v45
	v_exp_f32_e32 v53, v50
	s_nop 0
	v_pk_add_f32 v[50:51], v[52:53], 1.0 op_sel_hi:[1,0]
	s_nop 0
	s_nop 0
	v_rcp_f32_e32 v53, v51
	v_readlane_b32 s90, v255, 34
	v_readlane_b32 s91, v255, 35
	v_rcp_f32_e32 v59, v50
	v_cvt_pk_bf16_f32 v50, v54, v0
	v_cvt_pk_bf16_f32 v52, v56, v55
	v_mov_b64_e32 v[54:55], s[90:91]
	v_mad_i64_i32 v[54:55], s[90:91], v114, s39, v[54:55]
	v_lshl_add_u64 v[54:55], v[66:67], 1, v[54:55]
	v_add_co_u32_e32 v54, vcc, 0xfffff000, v54
	v_cvt_pk_bf16_f32 v51, v58, v57
	v_cvt_pk_bf16_f32 v53, v59, v53
	v_addc_co_u32_e32 v55, vcc, -1, v55, vcc
	s_mov_b64 s[90:91], 0
	global_store_dwordx4 v[54:55], v[50:53], off offset:-1024

; DI uint4 pack8(f32x4 a, f32x4 b) { uint4 r; r.x = pack2(a[0], a[1]); r.y = pack2(a[2], a[3]); r.z = pack2(b[0], b[1]); r.w = pack2(b[2], b[3]); return r; }
; DI float sigmoidf_(float x) { return 1.f / (1.f + __expf(-x)); }
;   DI void operator()(const Acc8& acc, const pg8::Unit& u, int wr, int wc, int fr, int fq) const {
;     ...
;           else {
; #pragma unroll
;             for (int e = 0; e < 4; ++e) { v0[e] = sigmoidf_(v0[e]); v1[e] = sigmoidf_(v1[e]); }
;             *(uint4*)(gates + (size_t)row * 3072 + (c8 - 2560)) = pack8(v0, v1);
.LBB0_946:
	s_and_b64 vcc, exec, s[10:11]
	s_cbranch_vccnz .LBB0_966
	s_andn2_b64 vcc, exec, s[66:67]
	s_cbranch_vccnz .LBB0_963
	s_andn2_b64 vcc, exec, s[48:49]
	s_cbranch_vccnz .LBB0_960
	s_andn2_b64 vcc, exec, s[70:71]
	s_cbranch_vccnz .LBB0_957
	s_andn2_b64 vcc, exec, s[68:69]
	s_cbranch_vccnz .LBB0_952
	v_mul_f32_e32 v0, 0xbfb8aa3b, v38
	v_exp_f32_e32 v42, v0
	v_mul_f32_e32 v0, 0xbfb8aa3b, v34
	v_exp_f32_e32 v44, v0
	v_mul_f32_e32 v0, 0xbfb8aa3b, v39
	v_exp_f32_e32 v43, v0
	s_movk_i32 s39, 0x1800
	v_pk_add_f32 v[42:43], v[42:43], 1.0 op_sel_hi:[1,0]
	s_nop 0
	s_nop 0
	v_rcp_f32_e32 v0, v43
	s_nop 0
	v_rcp_f32_e32 v46, v42
	v_mul_f32_e32 v42, 0xbfb8aa3b, v35
	v_exp_f32_e32 v45, v42
	s_nop 0
	v_pk_add_f32 v[42:43], v[44:45], 1.0 op_sel_hi:[1,0]
	s_nop 0
	s_nop 0
	v_rcp_f32_e32 v47, v43
	s_nop 0
	v_rcp_f32_e32 v48, v42
	v_mul_f32_e32 v43, 0xbfb8aa3b, v36
	v_mul_f32_e32 v42, 0xbfb8aa3b, v40
	v_exp_f32_e32 v44, v43
	v_mul_f32_e32 v43, 0xbfb8aa3b, v41
	v_exp_f32_e32 v42, v42
	v_exp_f32_e32 v43, v43
	s_nop 0
	v_pk_add_f32 v[42:43], v[42:43], 1.0 op_sel_hi:[1,0]
	s_nop 0
	s_nop 0
	v_rcp_f32_e32 v49, v43
	s_nop 0
	v_rcp_f32_e32 v50, v42
	v_mul_f32_e32 v42, 0xbfb8aa3b, v37
	v_exp_f32_e32 v45, v42
	s_nop 0
	v_pk_add_f32 v[42:43], v[44:45], 1.0 op_sel_hi:[1,0]
	s_nop 0
	s_nop 0
	v_rcp_f32_e32 v45, v43
	v_readlane_b32 s90, v255, 34
	v_readlane_b32 s91, v255, 35
	v_rcp_f32_e32 v51, v42
	v_cvt_pk_bf16_f32 v42, v46, v0
	v_cvt_pk_bf16_f32 v44, v48, v47
	v_mov_b64_e32 v[46:47], s[90:91]
	v_mad_i64_i32 v[46:47], s[90:91], v106, s39, v[46:47]
	v_lshl_add_u64 v[46:47], v[66:67], 1, v[46:47]
	v_add_co_u32_e32 v46, vcc, 0xfffff000, v46
	v_cvt_pk_bf16_f32 v43, v50, v49
	v_cvt_pk_bf16_f32 v45, v51, v45
	v_addc_co_u32_e32 v47, vcc, -1, v47, vcc
	s_mov_b64 s[90:91], 0
	global_store_dwordx4 v[46:47], v[42:45], off offset:-1024

; DI uint4 pack8(f32x4 a, f32x4 b) { uint4 r; r.x = pack2(a[0], a[1]); r.y = pack2(a[2], a[3]); r.z = pack2(b[0], b[1]); r.w = pack2(b[2], b[3]); return r; }
; DI float sigmoidf_(float x) { return 1.f / (1.f + __expf(-x)); }
;   DI void operator()(const Acc8& acc, const pg8::Unit& u, int wr, int wc, int fr, int fq) const {
;     ...
;           else {
; #pragma unroll
;             for (int e = 0; e < 4; ++e) { v0[e] = sigmoidf_(v0[e]); v1[e] = sigmoidf_(v1[e]); }
;             *(uint4*)(gates + (size_t)row * 3072 + (c8 - 2560)) = pack8(v0, v1);
.LBB0_978:
	s_and_b64 vcc, exec, s[10:11]
	s_cbranch_vccnz .LBB0_998
	s_andn2_b64 vcc, exec, s[66:67]
	s_cbranch_vccnz .LBB0_995
	s_andn2_b64 vcc, exec, s[48:49]
	s_cbranch_vccnz .LBB0_992
	s_andn2_b64 vcc, exec, s[70:71]
	s_cbranch_vccnz .LBB0_989
	s_andn2_b64 vcc, exec, s[68:69]
	s_cbranch_vccnz .LBB0_984
	v_mul_f32_e32 v0, 0xbfb8aa3b, v30
	v_exp_f32_e32 v34, v0
	v_mul_f32_e32 v0, 0xbfb8aa3b, v26
	v_exp_f32_e32 v36, v0
	v_mul_f32_e32 v0, 0xbfb8aa3b, v31
	v_exp_f32_e32 v35, v0
	s_movk_i32 s39, 0x1800
	v_pk_add_f32 v[34:35], v[34:35], 1.0 op_sel_hi:[1,0]
	s_nop 0
	s_nop 0
	v_rcp_f32_e32 v0, v35
	s_nop 0
	v_rcp_f32_e32 v38, v34
	v_mul_f32_e32 v34, 0xbfb8aa3b, v27
	v_exp_f32_e32 v37, v34
	s_nop 0
	v_pk_add_f32 v[34:35], v[36:37], 1.0 op_sel_hi:[1,0]
	s_nop 0
	s_nop 0
	v_rcp_f32_e32 v39, v35
	s_nop 0
	v_rcp_f32_e32 v40, v34
	v_mul_f32_e32 v35, 0xbfb8aa3b, v28
	v_mul_f32_e32 v34, 0xbfb8aa3b, v32
	v_exp_f32_e32 v36, v35
	v_mul_f32_e32 v35, 0xbfb8aa3b, v33
	v_exp_f32_e32 v34, v34
	v_exp_f32_e32 v35, v35
	s_nop 0
	v_pk_add_f32 v[34:35], v[34:35], 1.0 op_sel_hi:[1,0]
	s_nop 0
	s_nop 0
	v_rcp_f32_e32 v41, v35
	s_nop 0
	v_rcp_f32_e32 v42, v34
	v_mul_f32_e32 v34, 0xbfb8aa3b, v29
	v_exp_f32_e32 v37, v34
	s_nop 0
	v_pk_add_f32 v[34:35], v[36:37], 1.0 op_sel_hi:[1,0]
	s_nop 0
	s_nop 0
	v_rcp_f32_e32 v37, v35
	v_readlane_b32 s90, v255, 34
	v_readlane_b32 s91, v255, 35
	v_rcp_f32_e32 v43, v34
	v_cvt_pk_bf16_f32 v34, v38, v0
	v_cvt_pk_bf16_f32 v36, v40, v39
	v_mov_b64_e32 v[38:39], s[90:91]
	v_mad_i64_i32 v[38:39], s[90:91], v98, s39, v[38:39]
	v_lshl_add_u64 v[38:39], v[66:67], 1, v[38:39]
	v_add_co_u32_e32 v38, vcc, 0xfffff000, v38
	v_cvt_pk_bf16_f32 v35, v42, v41
	v_cvt_pk_bf16_f32 v37, v43, v37
	v_addc_co_u32_e32 v39, vcc, -1, v39, vcc
	s_mov_b64 s[90:91], 0
	global_store_dwordx4 v[38:39], v[34:37], off offset:-1024

; DI uint4 pack8(f32x4 a, f32x4 b) { uint4 r; r.x = pack2(a[0], a[1]); r.y = pack2(a[2], a[3]); r.z = pack2(b[0], b[1]); r.w = pack2(b[2], b[3]); return r; }
; DI float sigmoidf_(float x) { return 1.f / (1.f + __expf(-x)); }
;   DI void operator()(const Acc8& acc, const pg8::Unit& u, int wr, int wc, int fr, int fq) const {
;     ...
;           else {
; #pragma unroll
;             for (int e = 0; e < 4; ++e) { v0[e] = sigmoidf_(v0[e]); v1[e] = sigmoidf_(v1[e]); }
;             *(uint4*)(gates + (size_t)row * 3072 + (c8 - 2560)) = pack8(v0, v1);
.LBB0_1010:
	s_and_b64 vcc, exec, s[10:11]
	s_cbranch_vccnz .LBB0_1030
	s_andn2_b64 vcc, exec, s[66:67]
	s_cbranch_vccnz .LBB0_1027
	s_andn2_b64 vcc, exec, s[48:49]
	s_cbranch_vccnz .LBB0_1024
	s_andn2_b64 vcc, exec, s[70:71]
	s_cbranch_vccnz .LBB0_1021
	s_andn2_b64 vcc, exec, s[68:69]
	s_cbranch_vccnz .LBB0_1016
	v_mul_f32_e32 v0, 0xbfb8aa3b, v22
	v_exp_f32_e32 v26, v0
	v_mul_f32_e32 v0, 0xbfb8aa3b, v18
	v_exp_f32_e32 v28, v0
	v_mul_f32_e32 v0, 0xbfb8aa3b, v23
	v_exp_f32_e32 v27, v0
	s_movk_i32 s39, 0x1800
	v_pk_add_f32 v[26:27], v[26:27], 1.0 op_sel_hi:[1,0]
	s_nop 0
	s_nop 0
	v_rcp_f32_e32 v0, v27
	s_nop 0
	v_rcp_f32_e32 v30, v26
	v_mul_f32_e32 v26, 0xbfb8aa3b, v19
	v_exp_f32_e32 v29, v26
	s_nop 0
	v_pk_add_f32 v[26:27], v[28:29], 1.0 op_sel_hi:[1,0]
	s_nop 0
	s_nop 0
	v_rcp_f32_e32 v31, v27
	s_nop 0
	v_rcp_f32_e32 v32, v26
	v_mul_f32_e32 v27, 0xbfb8aa3b, v20
	v_mul_f32_e32 v26, 0xbfb8aa3b, v24
	v_exp_f32_e32 v28, v27
	v_mul_f32_e32 v27, 0xbfb8aa3b, v25
	v_exp_f32_e32 v26, v26
	v_exp_f32_e32 v27, v27
	s_nop 0
	v_pk_add_f32 v[26:27], v[26:27], 1.0 op_sel_hi:[1,0]
	s_nop 0
	s_nop 0
	v_rcp_f32_e32 v33, v27
	s_nop 0
	v_rcp_f32_e32 v34, v26
	v_mul_f32_e32 v26, 0xbfb8aa3b, v21
	v_exp_f32_e32 v29, v26
	s_nop 0
	v_pk_add_f32 v[26:27], v[28:29], 1.0 op_sel_hi:[1,0]
	s_nop 0
	s_nop 0
	v_rcp_f32_e32 v29, v27
	v_readlane_b32 s90, v255, 34
	v_readlane_b32 s91, v255, 35
	v_rcp_f32_e32 v35, v26
	v_cvt_pk_bf16_f32 v26, v30, v0
	v_cvt_pk_bf16_f32 v28, v32, v31
	v_mov_b64_e32 v[30:31], s[90:91]
	v_mad_i64_i32 v[30:31], s[90:91], v90, s39, v[30:31]
	v_lshl_add_u64 v[30:31], v[66:67], 1, v[30:31]
	v_add_co_u32_e32 v30, vcc, 0xfffff000, v30
	v_cvt_pk_bf16_f32 v27, v34, v33
	v_cvt_pk_bf16_f32 v29, v35, v29
	v_addc_co_u32_e32 v31, vcc, -1, v31, vcc
	s_mov_b64 s[90:91], 0
	global_store_dwordx4 v[30:31], v[26:29], off offset:-1024

; DI uint4 pack8(f32x4 a, f32x4 b) { uint4 r; r.x = pack2(a[0], a[1]); r.y = pack2(a[2], a[3]); r.z = pack2(b[0], b[1]); r.w = pack2(b[2], b[3]); return r; }
; DI float sigmoidf_(float x) { return 1.f / (1.f + __expf(-x)); }
;   DI void operator()(const Acc8& acc, const pg8::Unit& u, int wr, int wc, int fr, int fq) const {
;     ...
;           else {
; #pragma unroll
;             for (int e = 0; e < 4; ++e) { v0[e] = sigmoidf_(v0[e]); v1[e] = sigmoidf_(v1[e]); }
;             *(uint4*)(gates + (size_t)row * 3072 + (c8 - 2560)) = pack8(v0, v1);
.LBB0_1042:
	s_and_b64 vcc, exec, s[10:11]
	s_cbranch_vccnz .LBB0_1062
	s_andn2_b64 vcc, exec, s[66:67]
	s_cbranch_vccnz .LBB0_1059
	s_andn2_b64 vcc, exec, s[48:49]
	s_cbranch_vccnz .LBB0_1056
	s_andn2_b64 vcc, exec, s[70:71]
	s_cbranch_vccnz .LBB0_1053
	s_andn2_b64 vcc, exec, s[68:69]
	s_cbranch_vccnz .LBB0_1048
	v_mul_f32_e32 v0, 0xbfb8aa3b, v14
	v_exp_f32_e32 v18, v0
	v_mul_f32_e32 v0, 0xbfb8aa3b, v10
	v_exp_f32_e32 v20, v0
	v_mul_f32_e32 v0, 0xbfb8aa3b, v15
	v_exp_f32_e32 v19, v0
	s_movk_i32 s39, 0x1800
	v_pk_add_f32 v[18:19], v[18:19], 1.0 op_sel_hi:[1,0]
	s_nop 0
	s_nop 0
	v_rcp_f32_e32 v0, v19
	s_nop 0
	v_rcp_f32_e32 v22, v18
	v_mul_f32_e32 v18, 0xbfb8aa3b, v11
	v_exp_f32_e32 v21, v18
	s_nop 0
	v_pk_add_f32 v[18:19], v[20:21], 1.0 op_sel_hi:[1,0]
	s_nop 0
	s_nop 0
	v_rcp_f32_e32 v23, v19
	s_nop 0
	v_rcp_f32_e32 v24, v18
	v_mul_f32_e32 v19, 0xbfb8aa3b, v12
	v_mul_f32_e32 v18, 0xbfb8aa3b, v16
	v_exp_f32_e32 v20, v19
	v_mul_f32_e32 v19, 0xbfb8aa3b, v17
	v_exp_f32_e32 v18, v18
	v_exp_f32_e32 v19, v19
	s_nop 0
	v_pk_add_f32 v[18:19], v[18:19], 1.0 op_sel_hi:[1,0]
	s_nop 0
	s_nop 0
	v_rcp_f32_e32 v25, v19
	s_nop 0
	v_rcp_f32_e32 v26, v18
	v_mul_f32_e32 v18, 0xbfb8aa3b, v13
	v_exp_f32_e32 v21, v18
	s_nop 0
	v_pk_add_f32 v[18:19], v[20:21], 1.0 op_sel_hi:[1,0]
	s_nop 0
	s_nop 0
	v_rcp_f32_e32 v21, v19
	v_readlane_b32 s90, v255, 34
	v_readlane_b32 s91, v255, 35
	v_rcp_f32_e32 v27, v18
	v_cvt_pk_bf16_f32 v18, v22, v0
	v_cvt_pk_bf16_f32 v20, v24, v23
	v_mov_b64_e32 v[22:23], s[90:91]
	v_mad_i64_i32 v[22:23], s[90:91], v82, s39, v[22:23]
	v_lshl_add_u64 v[22:23], v[66:67], 1, v[22:23]
	v_add_co_u32_e32 v22, vcc, 0xfffff000, v22
	v_cvt_pk_bf16_f32 v19, v26, v25
	v_cvt_pk_bf16_f32 v21, v27, v21
	v_addc_co_u32_e32 v23, vcc, -1, v23, vcc
	s_mov_b64 s[90:91], 0
	global_store_dwordx4 v[22:23], v[18:21], off offset:-1024

; DI uint4 pack8(f32x4 a, f32x4 b) { uint4 r; r.x = pack2(a[0], a[1]); r.y = pack2(a[2], a[3]); r.z = pack2(b[0], b[1]); r.w = pack2(b[2], b[3]); return r; }
; DI float sigmoidf_(float x) { return 1.f / (1.f + __expf(-x)); }
;   DI void operator()(const Acc8& acc, const pg8::Unit& u, int wr, int wc, int fr, int fq) const {
;     ...
;           else {
; #pragma unroll
;             for (int e = 0; e < 4; ++e) { v0[e] = sigmoidf_(v0[e]); v1[e] = sigmoidf_(v1[e]); }
;             *(uint4*)(gates + (size_t)row * 3072 + (c8 - 2560)) = pack8(v0, v1);
.LBB0_1074:
	s_and_b64 vcc, exec, s[10:11]
	s_mov_b64 s[10:11], -1
	s_cbranch_vccnz .LBB0_1094
	s_andn2_b64 vcc, exec, s[66:67]
	s_cbranch_vccnz .LBB0_1091
	s_andn2_b64 vcc, exec, s[48:49]
	s_cbranch_vccnz .LBB0_1088
	s_andn2_b64 vcc, exec, s[70:71]
	s_cbranch_vccnz .LBB0_1085
	s_andn2_b64 vcc, exec, s[68:69]
	s_cbranch_vccnz .LBB0_1080
	v_mul_f32_e32 v0, 0xbfb8aa3b, v6
	v_exp_f32_e32 v10, v0
	v_mul_f32_e32 v0, 0xbfb8aa3b, v2
	v_exp_f32_e32 v12, v0
	v_mul_f32_e32 v0, 0xbfb8aa3b, v7
	v_exp_f32_e32 v11, v0
	s_nop 0
	v_pk_add_f32 v[10:11], v[10:11], 1.0 op_sel_hi:[1,0]
	s_nop 0
	s_nop 0
	v_rcp_f32_e32 v0, v11
	s_nop 0
	v_rcp_f32_e32 v14, v10
	v_mul_f32_e32 v10, 0xbfb8aa3b, v3
	v_exp_f32_e32 v13, v10
	s_nop 0
	v_pk_add_f32 v[10:11], v[12:13], 1.0 op_sel_hi:[1,0]
	s_nop 0
	s_nop 0
	v_rcp_f32_e32 v15, v11
	s_nop 0
	v_rcp_f32_e32 v16, v10
	v_mul_f32_e32 v11, 0xbfb8aa3b, v4
	v_mul_f32_e32 v10, 0xbfb8aa3b, v8
	v_exp_f32_e32 v12, v11
	v_mul_f32_e32 v11, 0xbfb8aa3b, v9
	v_exp_f32_e32 v10, v10
	v_exp_f32_e32 v11, v11
	s_nop 0
	v_pk_add_f32 v[10:11], v[10:11], 1.0 op_sel_hi:[1,0]
	s_nop 0
	s_nop 0
	v_rcp_f32_e32 v17, v11
	s_nop 0
	v_rcp_f32_e32 v18, v10
	v_mul_f32_e32 v10, 0xbfb8aa3b, v5
	v_exp_f32_e32 v13, v10
	s_nop 0
	v_pk_add_f32 v[10:11], v[12:13], 1.0 op_sel_hi:[1,0]
	s_nop 0
	s_nop 0
	v_rcp_f32_e32 v13, v11
	v_readlane_b32 s10, v255, 34
	v_readlane_b32 s11, v255, 35
	v_rcp_f32_e32 v19, v10
	v_cvt_pk_bf16_f32 v10, v14, v0
	v_cvt_pk_bf16_f32 v12, v16, v15
	v_mov_b64_e32 v[14:15], s[10:11]
	s_movk_i32 s10, 0x1800
	v_mad_i64_i32 v[14:15], s[10:11], v74, s10, v[14:15]
	v_lshl_add_u64 v[14:15], v[66:67], 1, v[14:15]
	v_add_co_u32_e32 v14, vcc, 0xfffff000, v14
	v_cvt_pk_bf16_f32 v11, v18, v17
	v_cvt_pk_bf16_f32 v13, v19, v13
	v_addc_co_u32_e32 v15, vcc, -1, v15, vcc
	s_mov_b64 s[10:11], 0
	global_store_dwordx4 v[14:15], v[10:13], off offset:-1024
